# wide residual loads (permlane16_swap), NSA final y stores widened to dwordx4, NSA compressed K/V tile loads issued back-to-back, dtype comment
# speedup vs baseline: 1.0582x; 1.0089x over previous
; DEVI float lo2f(unsigned u) { return __uint_as_float(u << 16); }
; DEVI float hi2f(unsigned u) { return __uint_as_float(u & 0xffff0000u); }
; DEVI void phase_resid_gemm(const Params& p, const bfu* A, int lda, int nkt, const bfu* wT, int ldb, const float* resid32,
;                            float* ssq_out, float* out32, char* lds) {
;     ...
;     for (int mi = 0; mi < 8; ++mi) {
;       const int m = m0 + wm * 128 + mi * 16 + fr;
;       float ss = 0.f;
; #pragma unroll
;       for (int ni = 0; ni < 4; ++ni) {
;         const int n = n0 + wn * 64 + ni * 16 + fq * 4;
;         float4 r;
;         if (resid32) r = *(const float4*)(resid32 + (long)m * 1024 + n);
;         else { const uint2 u = *(const uint2*)(xs + (long)m * LDX + n); r = make_float4(lo2f(u.x), hi2f(u.x), lo2f(u.y), hi2f(u.y)); }
;         float4 o;
;         o.x = r.x + acc[ni][mi][0]; o.y = r.y + acc[ni][mi][1]; o.z = r.z + acc[ni][mi][2]; o.w = r.w + acc[ni][mi][3];
;         if (out32) *(float4*)(out32 + (long)m * 1024 + n) = o;
;         else {
;           uint2 ob; ob.x = pack2(o.x, o.y); ob.y = pack2(o.z, o.w);
;           *(uint2*)(xs + (long)m * LDX + n) = ob;
;           const float q0 = lo2f(ob.x), q1 = hi2f(ob.x), q2 = lo2f(ob.y), q3 = hi2f(ob.y);
;           ss += q0 * q0 + q1 * q1 + q2 * q2 + q3 * q3;
.LBB0_38:
	s_lshl_b32 s20, s25, 8
	v_add_u32_e32 v132, s20, v179
	v_or_b32_e32 v130, s27, v181
	v_mov_b64_e32 v[126:127], s[2:3]
	v_mad_i64_i32 v[126:127], s[28:29], v132, s95, v[126:127]
	v_ashrrev_i32_e32 v131, 31, v130
	v_lshl_add_u64 v[134:135], v[130:131], 1, v[126:127]
	v_lshl_add_u64 v[218:219], v[134:135], 0, v[254:255]
	global_load_dwordx4 v[214:217], v[218:219], off
	v_ashrrev_i32_e32 v133, 31, v132
	v_lshlrev_b64 v[128:129], 12, v[132:133]
	v_cndmask_b32_e64 v0, 0, 1, s[46:47]
	v_lshl_add_u64 v[136:137], s[0:1], 0, v[128:129]
	s_mov_b64 s[36:37], -1
	v_cmp_ne_u32_e64 s[42:43], 1, v0
	s_andn2_b64 vcc, exec, s[46:47]
	v_lshl_add_u64 v[136:137], v[130:131], 2, v[136:137]
	s_waitcnt vmcnt(0)
	v_permlane16_swap_b32_e32 v214, v216
	v_permlane16_swap_b32_e32 v215, v217
	s_nop 1
	v_lshlrev_b32_e32 v128, 16, v214
	v_and_b32_e32 v129, 0xffff0000, v214
	v_lshlrev_b32_e32 v138, 16, v215
	v_and_b32_e32 v139, 0xffff0000, v215
	v_pk_add_f32 v[126:127], v[162:163], v[128:129]
	v_pk_add_f32 v[128:129], v[164:165], v[138:139]
	s_cbranch_vccnz .LBB0_40
	s_mov_b64 s[36:37], 0
	global_store_dwordx4 v[136:137], v[126:129], off

; DEVI float lo2f(unsigned u) { return __uint_as_float(u << 16); }
; DEVI float hi2f(unsigned u) { return __uint_as_float(u & 0xffff0000u); }
; DEVI void phase_resid_gemm(const Params& p, const bfu* A, int lda, int nkt, const bfu* wT, int ldb, const float* resid32,
;                            float* ssq_out, float* out32, char* lds) {
;     ...
;       for (int ni = 0; ni < 4; ++ni) {
;         const int n = n0 + wn * 64 + ni * 16 + fq * 4;
;         float4 r;
;         if (resid32) r = *(const float4*)(resid32 + (long)m * 1024 + n);
;         else { const uint2 u = *(const uint2*)(xs + (long)m * LDX + n); r = make_float4(lo2f(u.x), hi2f(u.x), lo2f(u.y), hi2f(u.y)); }
;         float4 o;
;         o.x = r.x + acc[ni][mi][0]; o.y = r.y + acc[ni][mi][1]; o.z = r.z + acc[ni][mi][2]; o.w = r.w + acc[ni][mi][3];
;         if (out32) *(float4*)(out32 + (long)m * 1024 + n) = o;
.LBB0_42:
	s_and_b64 vcc, exec, s[42:43]
	s_mov_b64 s[36:37], -1
	s_waitcnt vmcnt(0)
	v_lshlrev_b32_e32 v128, 16, v216
	v_and_b32_e32 v129, 0xffff0000, v216
	v_lshlrev_b32_e32 v126, 16, v217
	v_and_b32_e32 v127, 0xffff0000, v217
	v_pk_add_f32 v[122:123], v[122:123], v[128:129]
	v_pk_add_f32 v[124:125], v[124:125], v[126:127]
	s_cbranch_vccnz .LBB0_44
	s_mov_b64 s[36:37], 0
	global_store_dwordx4 v[136:137], v[122:125], off offset:64

; DEVI float lo2f(unsigned u) { return __uint_as_float(u << 16); }
; DEVI float hi2f(unsigned u) { return __uint_as_float(u & 0xffff0000u); }
; DEVI void phase_resid_gemm(const Params& p, const bfu* A, int lda, int nkt, const bfu* wT, int ldb, const float* resid32,
;                            float* ssq_out, float* out32, char* lds) {
;     ...
;       for (int ni = 0; ni < 4; ++ni) {
;         const int n = n0 + wn * 64 + ni * 16 + fq * 4;
;         float4 r;
;         if (resid32) r = *(const float4*)(resid32 + (long)m * 1024 + n);
;         else { const uint2 u = *(const uint2*)(xs + (long)m * LDX + n); r = make_float4(lo2f(u.x), hi2f(u.x), lo2f(u.y), hi2f(u.y)); }
;         float4 o;
;         o.x = r.x + acc[ni][mi][0]; o.y = r.y + acc[ni][mi][1]; o.z = r.z + acc[ni][mi][2]; o.w = r.w + acc[ni][mi][3];
;         if (out32) *(float4*)(out32 + (long)m * 1024 + n) = o;
.LBB0_46:
	v_lshl_add_u64 v[218:219], v[134:135], 0, v[254:255]
	global_load_dwordx4 v[214:217], v[218:219], off offset:64
	s_and_b64 vcc, exec, s[42:43]
	s_mov_b64 s[36:37], -1
	s_waitcnt vmcnt(0)
	v_permlane16_swap_b32_e32 v214, v216
	v_permlane16_swap_b32_e32 v215, v217
	s_nop 1
	v_lshlrev_b32_e32 v124, 16, v214
	v_and_b32_e32 v125, 0xffff0000, v214
	v_lshlrev_b32_e32 v122, 16, v215
	v_and_b32_e32 v123, 0xffff0000, v215
	v_pk_add_f32 v[114:115], v[114:115], v[124:125]
	v_pk_add_f32 v[116:117], v[116:117], v[122:123]
	s_cbranch_vccnz .LBB0_48
	s_mov_b64 s[36:37], 0
	global_store_dwordx4 v[136:137], v[114:117], off offset:128

; DEVI float lo2f(unsigned u) { return __uint_as_float(u << 16); }
; DEVI float hi2f(unsigned u) { return __uint_as_float(u & 0xffff0000u); }
; DEVI void phase_resid_gemm(const Params& p, const bfu* A, int lda, int nkt, const bfu* wT, int ldb, const float* resid32,
;                            float* ssq_out, float* out32, char* lds) {
;     ...
;       for (int ni = 0; ni < 4; ++ni) {
;         const int n = n0 + wn * 64 + ni * 16 + fq * 4;
;         float4 r;
;         if (resid32) r = *(const float4*)(resid32 + (long)m * 1024 + n);
;         else { const uint2 u = *(const uint2*)(xs + (long)m * LDX + n); r = make_float4(lo2f(u.x), hi2f(u.x), lo2f(u.y), hi2f(u.y)); }
;         float4 o;
;         o.x = r.x + acc[ni][mi][0]; o.y = r.y + acc[ni][mi][1]; o.z = r.z + acc[ni][mi][2]; o.w = r.w + acc[ni][mi][3];
;         if (out32) *(float4*)(out32 + (long)m * 1024 + n) = o;
.LBB0_50:
	s_and_b64 vcc, exec, s[42:43]
	s_mov_b64 s[36:37], -1
	s_waitcnt vmcnt(0)
	v_lshlrev_b32_e32 v116, 16, v216
	v_and_b32_e32 v117, 0xffff0000, v216
	v_lshlrev_b32_e32 v114, 16, v217
	v_and_b32_e32 v115, 0xffff0000, v217
	v_pk_add_f32 v[110:111], v[110:111], v[116:117]
	v_pk_add_f32 v[112:113], v[112:113], v[114:115]
	s_cbranch_vccz .LBB0_53
	s_andn2_b64 vcc, exec, s[36:37]
	s_cbranch_vccz .LBB0_54

; DEVI float lo2f(unsigned u) { return __uint_as_float(u << 16); }
; DEVI float hi2f(unsigned u) { return __uint_as_float(u & 0xffff0000u); }
; DEVI void phase_resid_gemm(const Params& p, const bfu* A, int lda, int nkt, const bfu* wT, int ldb, const float* resid32,
;                            float* ssq_out, float* out32, char* lds) {
;     ...
;       const int m = m0 + wm * 128 + mi * 16 + fr;
;       float ss = 0.f;
; #pragma unroll
;       for (int ni = 0; ni < 4; ++ni) {
;         const int n = n0 + wn * 64 + ni * 16 + fq * 4;
;         float4 r;
;         if (resid32) r = *(const float4*)(resid32 + (long)m * 1024 + n);
;         else { const uint2 u = *(const uint2*)(xs + (long)m * LDX + n); r = make_float4(lo2f(u.x), hi2f(u.x), lo2f(u.y), hi2f(u.y)); }
;         float4 o;
;         o.x = r.x + acc[ni][mi][0]; o.y = r.y + acc[ni][mi][1]; o.z = r.z + acc[ni][mi][2]; o.w = r.w + acc[ni][mi][3];
;         if (out32) *(float4*)(out32 + (long)m * 1024 + n) = o;
.LBB0_58:
	s_waitcnt lgkmcnt(0)
	v_or_b32_e32 v110, 16, v132
	v_mov_b64_e32 v[112:113], s[2:3]
	v_mad_i64_i32 v[112:113], s[28:29], v110, s95, v[112:113]
	v_lshl_add_u64 v[114:115], v[130:131], 1, v[112:113]
	v_lshl_add_u64 v[218:219], v[114:115], 0, v[254:255]
	global_load_dwordx4 v[214:217], v[218:219], off
	v_ashrrev_i32_e32 v111, 31, v110
	v_lshlrev_b64 v[110:111], 12, v[110:111]
	v_lshl_add_u64 v[116:117], s[0:1], 0, v[110:111]
	s_mov_b64 s[36:37], -1
	s_and_b64 vcc, exec, s[42:43]
	v_lshl_add_u64 v[116:117], v[130:131], 2, v[116:117]
	s_waitcnt vmcnt(0)
	v_permlane16_swap_b32_e32 v214, v216
	v_permlane16_swap_b32_e32 v215, v217
	s_nop 1
	v_lshlrev_b32_e32 v110, 16, v214
	v_and_b32_e32 v111, 0xffff0000, v214
	v_lshlrev_b32_e32 v112, 16, v215
	v_and_b32_e32 v113, 0xffff0000, v215
	v_pk_add_f32 v[110:111], v[118:119], v[110:111]
	v_pk_add_f32 v[112:113], v[120:121], v[112:113]
	s_cbranch_vccnz .LBB0_60
	s_mov_b64 s[36:37], 0
	global_store_dwordx4 v[116:117], v[110:113], off

; DEVI float lo2f(unsigned u) { return __uint_as_float(u << 16); }
; DEVI float hi2f(unsigned u) { return __uint_as_float(u & 0xffff0000u); }
; DEVI void phase_resid_gemm(const Params& p, const bfu* A, int lda, int nkt, const bfu* wT, int ldb, const float* resid32,
;                            float* ssq_out, float* out32, char* lds) {
;     ...
;       for (int ni = 0; ni < 4; ++ni) {
;         const int n = n0 + wn * 64 + ni * 16 + fq * 4;
;         float4 r;
;         if (resid32) r = *(const float4*)(resid32 + (long)m * 1024 + n);
;         else { const uint2 u = *(const uint2*)(xs + (long)m * LDX + n); r = make_float4(lo2f(u.x), hi2f(u.x), lo2f(u.y), hi2f(u.y)); }
;         float4 o;
;         o.x = r.x + acc[ni][mi][0]; o.y = r.y + acc[ni][mi][1]; o.z = r.z + acc[ni][mi][2]; o.w = r.w + acc[ni][mi][3];
;         if (out32) *(float4*)(out32 + (long)m * 1024 + n) = o;
.LBB0_62:
	s_and_b64 vcc, exec, s[42:43]
	s_mov_b64 s[36:37], -1
	s_waitcnt vmcnt(0)
	v_lshlrev_b32_e32 v112, 16, v216
	v_and_b32_e32 v113, 0xffff0000, v216
	v_lshlrev_b32_e32 v110, 16, v217
	v_and_b32_e32 v111, 0xffff0000, v217
	v_pk_add_f32 v[106:107], v[106:107], v[112:113]
	v_pk_add_f32 v[108:109], v[108:109], v[110:111]
	s_cbranch_vccnz .LBB0_64
	s_mov_b64 s[36:37], 0
	global_store_dwordx4 v[116:117], v[106:109], off offset:64

; DEVI float lo2f(unsigned u) { return __uint_as_float(u << 16); }
; DEVI float hi2f(unsigned u) { return __uint_as_float(u & 0xffff0000u); }
; DEVI void phase_resid_gemm(const Params& p, const bfu* A, int lda, int nkt, const bfu* wT, int ldb, const float* resid32,
;                            float* ssq_out, float* out32, char* lds) {
;     ...
;       for (int ni = 0; ni < 4; ++ni) {
;         const int n = n0 + wn * 64 + ni * 16 + fq * 4;
;         float4 r;
;         if (resid32) r = *(const float4*)(resid32 + (long)m * 1024 + n);
;         else { const uint2 u = *(const uint2*)(xs + (long)m * LDX + n); r = make_float4(lo2f(u.x), hi2f(u.x), lo2f(u.y), hi2f(u.y)); }
;         float4 o;
;         o.x = r.x + acc[ni][mi][0]; o.y = r.y + acc[ni][mi][1]; o.z = r.z + acc[ni][mi][2]; o.w = r.w + acc[ni][mi][3];
;         if (out32) *(float4*)(out32 + (long)m * 1024 + n) = o;
.LBB0_66:
	v_lshl_add_u64 v[218:219], v[114:115], 0, v[254:255]
	global_load_dwordx4 v[214:217], v[218:219], off offset:64
	s_and_b64 vcc, exec, s[42:43]
	s_mov_b64 s[36:37], -1
	s_waitcnt vmcnt(0)
	v_permlane16_swap_b32_e32 v214, v216
	v_permlane16_swap_b32_e32 v215, v217
	s_nop 1
	v_lshlrev_b32_e32 v108, 16, v214
	v_and_b32_e32 v109, 0xffff0000, v214
	v_lshlrev_b32_e32 v106, 16, v215
	v_and_b32_e32 v107, 0xffff0000, v215
	v_pk_add_f32 v[102:103], v[102:103], v[108:109]
	v_pk_add_f32 v[104:105], v[104:105], v[106:107]
	s_cbranch_vccnz .LBB0_68
	s_mov_b64 s[36:37], 0
	global_store_dwordx4 v[116:117], v[102:105], off offset:128

; DEVI float lo2f(unsigned u) { return __uint_as_float(u << 16); }
; DEVI float hi2f(unsigned u) { return __uint_as_float(u & 0xffff0000u); }
; DEVI void phase_resid_gemm(const Params& p, const bfu* A, int lda, int nkt, const bfu* wT, int ldb, const float* resid32,
;                            float* ssq_out, float* out32, char* lds) {
;     ...
;       for (int ni = 0; ni < 4; ++ni) {
;         const int n = n0 + wn * 64 + ni * 16 + fq * 4;
;         float4 r;
;         if (resid32) r = *(const float4*)(resid32 + (long)m * 1024 + n);
;         else { const uint2 u = *(const uint2*)(xs + (long)m * LDX + n); r = make_float4(lo2f(u.x), hi2f(u.x), lo2f(u.y), hi2f(u.y)); }
;         float4 o;
;         o.x = r.x + acc[ni][mi][0]; o.y = r.y + acc[ni][mi][1]; o.z = r.z + acc[ni][mi][2]; o.w = r.w + acc[ni][mi][3];
;         if (out32) *(float4*)(out32 + (long)m * 1024 + n) = o;
.LBB0_70:
	s_and_b64 vcc, exec, s[42:43]
	s_mov_b64 s[36:37], -1
	s_waitcnt vmcnt(0)
	v_lshlrev_b32_e32 v104, 16, v216
	v_and_b32_e32 v105, 0xffff0000, v216
	v_lshlrev_b32_e32 v102, 16, v217
	v_and_b32_e32 v103, 0xffff0000, v217
	v_pk_add_f32 v[94:95], v[94:95], v[104:105]
	v_pk_add_f32 v[96:97], v[96:97], v[102:103]
	s_cbranch_vccz .LBB0_73
	s_andn2_b64 vcc, exec, s[36:37]
	s_cbranch_vccz .LBB0_74

; DEVI float lo2f(unsigned u) { return __uint_as_float(u << 16); }
; DEVI float hi2f(unsigned u) { return __uint_as_float(u & 0xffff0000u); }
; DEVI void phase_resid_gemm(const Params& p, const bfu* A, int lda, int nkt, const bfu* wT, int ldb, const float* resid32,
;                            float* ssq_out, float* out32, char* lds) {
;     ...
;       const int m = m0 + wm * 128 + mi * 16 + fr;
;       float ss = 0.f;
; #pragma unroll
;       for (int ni = 0; ni < 4; ++ni) {
;         const int n = n0 + wn * 64 + ni * 16 + fq * 4;
;         float4 r;
;         if (resid32) r = *(const float4*)(resid32 + (long)m * 1024 + n);
;         else { const uint2 u = *(const uint2*)(xs + (long)m * LDX + n); r = make_float4(lo2f(u.x), hi2f(u.x), lo2f(u.y), hi2f(u.y)); }
;         float4 o;
;         o.x = r.x + acc[ni][mi][0]; o.y = r.y + acc[ni][mi][1]; o.z = r.z + acc[ni][mi][2]; o.w = r.w + acc[ni][mi][3];
;         if (out32) *(float4*)(out32 + (long)m * 1024 + n) = o;
.LBB0_78:
	s_waitcnt lgkmcnt(0)
	v_or_b32_e32 v94, 32, v132
	v_mov_b64_e32 v[96:97], s[2:3]
	v_mad_i64_i32 v[96:97], s[28:29], v94, s95, v[96:97]
	v_lshl_add_u64 v[102:103], v[130:131], 1, v[96:97]
	v_lshl_add_u64 v[218:219], v[102:103], 0, v[254:255]
	global_load_dwordx4 v[214:217], v[218:219], off
	v_ashrrev_i32_e32 v95, 31, v94
	v_lshlrev_b64 v[94:95], 12, v[94:95]
	v_lshl_add_u64 v[104:105], s[0:1], 0, v[94:95]
	s_mov_b64 s[36:37], -1
	s_and_b64 vcc, exec, s[42:43]
	s_waitcnt vmcnt(0)
	v_permlane16_swap_b32_e32 v214, v216
	v_permlane16_swap_b32_e32 v215, v217
	s_nop 1
	v_lshlrev_b32_e32 v94, 16, v214
	v_and_b32_e32 v95, 0xffff0000, v214
	v_lshlrev_b32_e32 v96, 16, v215
	v_and_b32_e32 v97, 0xffff0000, v215
	v_pk_add_f32 v[94:95], v[98:99], v[94:95]
	v_pk_add_f32 v[96:97], v[100:101], v[96:97]
	v_lshl_add_u64 v[98:99], v[130:131], 2, v[104:105]
	s_cbranch_vccnz .LBB0_80
	s_mov_b64 s[36:37], 0
	global_store_dwordx4 v[98:99], v[94:97], off

; DEVI float lo2f(unsigned u) { return __uint_as_float(u << 16); }
; DEVI float hi2f(unsigned u) { return __uint_as_float(u & 0xffff0000u); }
; DEVI void phase_resid_gemm(const Params& p, const bfu* A, int lda, int nkt, const bfu* wT, int ldb, const float* resid32,
;                            float* ssq_out, float* out32, char* lds) {
;     ...
;       for (int ni = 0; ni < 4; ++ni) {
;         const int n = n0 + wn * 64 + ni * 16 + fq * 4;
;         float4 r;
;         if (resid32) r = *(const float4*)(resid32 + (long)m * 1024 + n);
;         else { const uint2 u = *(const uint2*)(xs + (long)m * LDX + n); r = make_float4(lo2f(u.x), hi2f(u.x), lo2f(u.y), hi2f(u.y)); }
;         float4 o;
;         o.x = r.x + acc[ni][mi][0]; o.y = r.y + acc[ni][mi][1]; o.z = r.z + acc[ni][mi][2]; o.w = r.w + acc[ni][mi][3];
;         if (out32) *(float4*)(out32 + (long)m * 1024 + n) = o;
.LBB0_82:
	s_and_b64 vcc, exec, s[42:43]
	s_mov_b64 s[36:37], -1
	s_waitcnt vmcnt(0)
	v_lshlrev_b32_e32 v96, 16, v216
	v_and_b32_e32 v97, 0xffff0000, v216
	v_lshlrev_b32_e32 v94, 16, v217
	v_and_b32_e32 v95, 0xffff0000, v217
	v_pk_add_f32 v[90:91], v[90:91], v[96:97]
	v_pk_add_f32 v[92:93], v[92:93], v[94:95]
	s_cbranch_vccnz .LBB0_84
	s_mov_b64 s[36:37], 0
	global_store_dwordx4 v[98:99], v[90:93], off offset:64

; DEVI float lo2f(unsigned u) { return __uint_as_float(u << 16); }
; DEVI float hi2f(unsigned u) { return __uint_as_float(u & 0xffff0000u); }
; DEVI void phase_resid_gemm(const Params& p, const bfu* A, int lda, int nkt, const bfu* wT, int ldb, const float* resid32,
;                            float* ssq_out, float* out32, char* lds) {
;     ...
;       for (int ni = 0; ni < 4; ++ni) {
;         const int n = n0 + wn * 64 + ni * 16 + fq * 4;
;         float4 r;
;         if (resid32) r = *(const float4*)(resid32 + (long)m * 1024 + n);
;         else { const uint2 u = *(const uint2*)(xs + (long)m * LDX + n); r = make_float4(lo2f(u.x), hi2f(u.x), lo2f(u.y), hi2f(u.y)); }
;         float4 o;
;         o.x = r.x + acc[ni][mi][0]; o.y = r.y + acc[ni][mi][1]; o.z = r.z + acc[ni][mi][2]; o.w = r.w + acc[ni][mi][3];
;         if (out32) *(float4*)(out32 + (long)m * 1024 + n) = o;
.LBB0_86:
	v_lshl_add_u64 v[218:219], v[102:103], 0, v[254:255]
	global_load_dwordx4 v[214:217], v[218:219], off offset:64
	s_and_b64 vcc, exec, s[42:43]
	s_mov_b64 s[36:37], -1
	s_waitcnt vmcnt(0)
	v_permlane16_swap_b32_e32 v214, v216
	v_permlane16_swap_b32_e32 v215, v217
	s_nop 1
	v_lshlrev_b32_e32 v92, 16, v214
	v_and_b32_e32 v93, 0xffff0000, v214
	v_lshlrev_b32_e32 v90, 16, v215
	v_and_b32_e32 v91, 0xffff0000, v215
	v_pk_add_f32 v[86:87], v[86:87], v[92:93]
	v_pk_add_f32 v[88:89], v[88:89], v[90:91]
	s_cbranch_vccnz .LBB0_88
	s_mov_b64 s[36:37], 0
	global_store_dwordx4 v[98:99], v[86:89], off offset:128

; DEVI float lo2f(unsigned u) { return __uint_as_float(u << 16); }
; DEVI float hi2f(unsigned u) { return __uint_as_float(u & 0xffff0000u); }
; DEVI void phase_resid_gemm(const Params& p, const bfu* A, int lda, int nkt, const bfu* wT, int ldb, const float* resid32,
;                            float* ssq_out, float* out32, char* lds) {
;     ...
;       for (int ni = 0; ni < 4; ++ni) {
;         const int n = n0 + wn * 64 + ni * 16 + fq * 4;
;         float4 r;
;         if (resid32) r = *(const float4*)(resid32 + (long)m * 1024 + n);
;         else { const uint2 u = *(const uint2*)(xs + (long)m * LDX + n); r = make_float4(lo2f(u.x), hi2f(u.x), lo2f(u.y), hi2f(u.y)); }
;         float4 o;
;         o.x = r.x + acc[ni][mi][0]; o.y = r.y + acc[ni][mi][1]; o.z = r.z + acc[ni][mi][2]; o.w = r.w + acc[ni][mi][3];
;         if (out32) *(float4*)(out32 + (long)m * 1024 + n) = o;
.LBB0_90:
	s_and_b64 vcc, exec, s[42:43]
	s_mov_b64 s[36:37], -1
	s_waitcnt vmcnt(0)
	v_lshlrev_b32_e32 v88, 16, v216
	v_and_b32_e32 v89, 0xffff0000, v216
	v_lshlrev_b32_e32 v86, 16, v217
	v_and_b32_e32 v87, 0xffff0000, v217
	v_pk_add_f32 v[78:79], v[78:79], v[88:89]
	v_pk_add_f32 v[80:81], v[80:81], v[86:87]
	s_cbranch_vccz .LBB0_93
	s_andn2_b64 vcc, exec, s[36:37]
	s_cbranch_vccz .LBB0_94

; DEVI float lo2f(unsigned u) { return __uint_as_float(u << 16); }
; DEVI float hi2f(unsigned u) { return __uint_as_float(u & 0xffff0000u); }
; DEVI void phase_resid_gemm(const Params& p, const bfu* A, int lda, int nkt, const bfu* wT, int ldb, const float* resid32,
;                            float* ssq_out, float* out32, char* lds) {
;     ...
;       const int m = m0 + wm * 128 + mi * 16 + fr;
;       float ss = 0.f;
; #pragma unroll
;       for (int ni = 0; ni < 4; ++ni) {
;         const int n = n0 + wn * 64 + ni * 16 + fq * 4;
;         float4 r;
;         if (resid32) r = *(const float4*)(resid32 + (long)m * 1024 + n);
;         else { const uint2 u = *(const uint2*)(xs + (long)m * LDX + n); r = make_float4(lo2f(u.x), hi2f(u.x), lo2f(u.y), hi2f(u.y)); }
;         float4 o;
;         o.x = r.x + acc[ni][mi][0]; o.y = r.y + acc[ni][mi][1]; o.z = r.z + acc[ni][mi][2]; o.w = r.w + acc[ni][mi][3];
;         if (out32) *(float4*)(out32 + (long)m * 1024 + n) = o;
.LBB0_98:
	s_waitcnt lgkmcnt(0)
	v_or_b32_e32 v78, 48, v132
	v_mov_b64_e32 v[80:81], s[2:3]
	v_mad_i64_i32 v[80:81], s[28:29], v78, s95, v[80:81]
	v_lshl_add_u64 v[86:87], v[130:131], 1, v[80:81]
	v_lshl_add_u64 v[218:219], v[86:87], 0, v[254:255]
	global_load_dwordx4 v[214:217], v[218:219], off
	v_ashrrev_i32_e32 v79, 31, v78
	v_lshlrev_b64 v[78:79], 12, v[78:79]
	v_lshl_add_u64 v[88:89], s[0:1], 0, v[78:79]
	s_mov_b64 s[36:37], -1
	s_and_b64 vcc, exec, s[42:43]
	s_waitcnt vmcnt(0)
	v_permlane16_swap_b32_e32 v214, v216
	v_permlane16_swap_b32_e32 v215, v217
	s_nop 1
	v_lshlrev_b32_e32 v78, 16, v214
	v_and_b32_e32 v79, 0xffff0000, v214
	v_lshlrev_b32_e32 v80, 16, v215
	v_and_b32_e32 v81, 0xffff0000, v215
	v_pk_add_f32 v[78:79], v[82:83], v[78:79]
	v_pk_add_f32 v[80:81], v[84:85], v[80:81]
	v_lshl_add_u64 v[82:83], v[130:131], 2, v[88:89]
	s_cbranch_vccnz .LBB0_100
	s_mov_b64 s[36:37], 0
	global_store_dwordx4 v[82:83], v[78:81], off

; DEVI float lo2f(unsigned u) { return __uint_as_float(u << 16); }
; DEVI float hi2f(unsigned u) { return __uint_as_float(u & 0xffff0000u); }
; DEVI void phase_resid_gemm(const Params& p, const bfu* A, int lda, int nkt, const bfu* wT, int ldb, const float* resid32,
;                            float* ssq_out, float* out32, char* lds) {
;     ...
;       for (int ni = 0; ni < 4; ++ni) {
;         const int n = n0 + wn * 64 + ni * 16 + fq * 4;
;         float4 r;
;         if (resid32) r = *(const float4*)(resid32 + (long)m * 1024 + n);
;         else { const uint2 u = *(const uint2*)(xs + (long)m * LDX + n); r = make_float4(lo2f(u.x), hi2f(u.x), lo2f(u.y), hi2f(u.y)); }
;         float4 o;
;         o.x = r.x + acc[ni][mi][0]; o.y = r.y + acc[ni][mi][1]; o.z = r.z + acc[ni][mi][2]; o.w = r.w + acc[ni][mi][3];
;         if (out32) *(float4*)(out32 + (long)m * 1024 + n) = o;
.LBB0_102:
	s_and_b64 vcc, exec, s[42:43]
	s_mov_b64 s[36:37], -1
	s_waitcnt vmcnt(0)
	v_lshlrev_b32_e32 v80, 16, v216
	v_and_b32_e32 v81, 0xffff0000, v216
	v_lshlrev_b32_e32 v78, 16, v217
	v_and_b32_e32 v79, 0xffff0000, v217
	v_pk_add_f32 v[74:75], v[74:75], v[80:81]
	v_pk_add_f32 v[76:77], v[76:77], v[78:79]
	s_cbranch_vccnz .LBB0_104
	s_mov_b64 s[36:37], 0
	global_store_dwordx4 v[82:83], v[74:77], off offset:64

; DEVI float lo2f(unsigned u) { return __uint_as_float(u << 16); }
; DEVI float hi2f(unsigned u) { return __uint_as_float(u & 0xffff0000u); }
; DEVI void phase_resid_gemm(const Params& p, const bfu* A, int lda, int nkt, const bfu* wT, int ldb, const float* resid32,
;                            float* ssq_out, float* out32, char* lds) {
;     ...
;       for (int ni = 0; ni < 4; ++ni) {
;         const int n = n0 + wn * 64 + ni * 16 + fq * 4;
;         float4 r;
;         if (resid32) r = *(const float4*)(resid32 + (long)m * 1024 + n);
;         else { const uint2 u = *(const uint2*)(xs + (long)m * LDX + n); r = make_float4(lo2f(u.x), hi2f(u.x), lo2f(u.y), hi2f(u.y)); }
;         float4 o;
;         o.x = r.x + acc[ni][mi][0]; o.y = r.y + acc[ni][mi][1]; o.z = r.z + acc[ni][mi][2]; o.w = r.w + acc[ni][mi][3];
;         if (out32) *(float4*)(out32 + (long)m * 1024 + n) = o;
.LBB0_106:
	v_lshl_add_u64 v[218:219], v[86:87], 0, v[254:255]
	global_load_dwordx4 v[214:217], v[218:219], off offset:64
	s_and_b64 vcc, exec, s[42:43]
	s_mov_b64 s[36:37], -1
	s_waitcnt vmcnt(0)
	v_permlane16_swap_b32_e32 v214, v216
	v_permlane16_swap_b32_e32 v215, v217
	s_nop 1
	v_lshlrev_b32_e32 v76, 16, v214
	v_and_b32_e32 v77, 0xffff0000, v214
	v_lshlrev_b32_e32 v74, 16, v215
	v_and_b32_e32 v75, 0xffff0000, v215
	v_pk_add_f32 v[70:71], v[70:71], v[76:77]
	v_pk_add_f32 v[72:73], v[72:73], v[74:75]
	s_cbranch_vccnz .LBB0_108
	s_mov_b64 s[36:37], 0
	global_store_dwordx4 v[82:83], v[70:73], off offset:128

; DEVI float lo2f(unsigned u) { return __uint_as_float(u << 16); }
; DEVI float hi2f(unsigned u) { return __uint_as_float(u & 0xffff0000u); }
; DEVI void phase_resid_gemm(const Params& p, const bfu* A, int lda, int nkt, const bfu* wT, int ldb, const float* resid32,
;                            float* ssq_out, float* out32, char* lds) {
;     ...
;       for (int ni = 0; ni < 4; ++ni) {
;         const int n = n0 + wn * 64 + ni * 16 + fq * 4;
;         float4 r;
;         if (resid32) r = *(const float4*)(resid32 + (long)m * 1024 + n);
;         else { const uint2 u = *(const uint2*)(xs + (long)m * LDX + n); r = make_float4(lo2f(u.x), hi2f(u.x), lo2f(u.y), hi2f(u.y)); }
;         float4 o;
;         o.x = r.x + acc[ni][mi][0]; o.y = r.y + acc[ni][mi][1]; o.z = r.z + acc[ni][mi][2]; o.w = r.w + acc[ni][mi][3];
;         if (out32) *(float4*)(out32 + (long)m * 1024 + n) = o;
.LBB0_110:
	s_and_b64 vcc, exec, s[42:43]
	s_mov_b64 s[36:37], -1
	s_waitcnt vmcnt(0)
	v_lshlrev_b32_e32 v72, 16, v216
	v_and_b32_e32 v73, 0xffff0000, v216
	v_lshlrev_b32_e32 v70, 16, v217
	v_and_b32_e32 v71, 0xffff0000, v217
	v_pk_add_f32 v[62:63], v[62:63], v[72:73]
	v_pk_add_f32 v[64:65], v[64:65], v[70:71]
	s_cbranch_vccz .LBB0_113
	s_andn2_b64 vcc, exec, s[36:37]
	s_cbranch_vccz .LBB0_114

; DEVI float lo2f(unsigned u) { return __uint_as_float(u << 16); }
; DEVI float hi2f(unsigned u) { return __uint_as_float(u & 0xffff0000u); }
; DEVI void phase_resid_gemm(const Params& p, const bfu* A, int lda, int nkt, const bfu* wT, int ldb, const float* resid32,
;                            float* ssq_out, float* out32, char* lds) {
;     ...
;       const int m = m0 + wm * 128 + mi * 16 + fr;
;       float ss = 0.f;
; #pragma unroll
;       for (int ni = 0; ni < 4; ++ni) {
;         const int n = n0 + wn * 64 + ni * 16 + fq * 4;
;         float4 r;
;         if (resid32) r = *(const float4*)(resid32 + (long)m * 1024 + n);
;         else { const uint2 u = *(const uint2*)(xs + (long)m * LDX + n); r = make_float4(lo2f(u.x), hi2f(u.x), lo2f(u.y), hi2f(u.y)); }
;         float4 o;
;         o.x = r.x + acc[ni][mi][0]; o.y = r.y + acc[ni][mi][1]; o.z = r.z + acc[ni][mi][2]; o.w = r.w + acc[ni][mi][3];
;         if (out32) *(float4*)(out32 + (long)m * 1024 + n) = o;
.LBB0_118:
	s_waitcnt lgkmcnt(0)
	v_or_b32_e32 v62, 64, v132
	v_mov_b64_e32 v[64:65], s[2:3]
	v_mad_i64_i32 v[64:65], s[28:29], v62, s95, v[64:65]
	v_lshl_add_u64 v[70:71], v[130:131], 1, v[64:65]
	v_lshl_add_u64 v[218:219], v[70:71], 0, v[254:255]
	global_load_dwordx4 v[214:217], v[218:219], off
	v_ashrrev_i32_e32 v63, 31, v62
	v_lshlrev_b64 v[62:63], 12, v[62:63]
	v_lshl_add_u64 v[72:73], s[0:1], 0, v[62:63]
	s_mov_b64 s[36:37], -1
	s_and_b64 vcc, exec, s[42:43]
	s_waitcnt vmcnt(0)
	v_permlane16_swap_b32_e32 v214, v216
	v_permlane16_swap_b32_e32 v215, v217
	s_nop 1
	v_lshlrev_b32_e32 v62, 16, v214
	v_and_b32_e32 v63, 0xffff0000, v214
	v_lshlrev_b32_e32 v64, 16, v215
	v_and_b32_e32 v65, 0xffff0000, v215
	v_pk_add_f32 v[62:63], v[66:67], v[62:63]
	v_pk_add_f32 v[64:65], v[68:69], v[64:65]
	v_lshl_add_u64 v[66:67], v[130:131], 2, v[72:73]
	s_cbranch_vccnz .LBB0_120
	s_mov_b64 s[36:37], 0
	global_store_dwordx4 v[66:67], v[62:65], off

; DEVI float lo2f(unsigned u) { return __uint_as_float(u << 16); }
; DEVI float hi2f(unsigned u) { return __uint_as_float(u & 0xffff0000u); }
; DEVI void phase_resid_gemm(const Params& p, const bfu* A, int lda, int nkt, const bfu* wT, int ldb, const float* resid32,
;                            float* ssq_out, float* out32, char* lds) {
;     ...
;       for (int ni = 0; ni < 4; ++ni) {
;         const int n = n0 + wn * 64 + ni * 16 + fq * 4;
;         float4 r;
;         if (resid32) r = *(const float4*)(resid32 + (long)m * 1024 + n);
;         else { const uint2 u = *(const uint2*)(xs + (long)m * LDX + n); r = make_float4(lo2f(u.x), hi2f(u.x), lo2f(u.y), hi2f(u.y)); }
;         float4 o;
;         o.x = r.x + acc[ni][mi][0]; o.y = r.y + acc[ni][mi][1]; o.z = r.z + acc[ni][mi][2]; o.w = r.w + acc[ni][mi][3];
;         if (out32) *(float4*)(out32 + (long)m * 1024 + n) = o;
.LBB0_122:
	s_and_b64 vcc, exec, s[42:43]
	s_mov_b64 s[36:37], -1
	s_waitcnt vmcnt(0)
	v_lshlrev_b32_e32 v64, 16, v216
	v_and_b32_e32 v65, 0xffff0000, v216
	v_lshlrev_b32_e32 v62, 16, v217
	v_and_b32_e32 v63, 0xffff0000, v217
	v_pk_add_f32 v[58:59], v[58:59], v[64:65]
	v_pk_add_f32 v[60:61], v[60:61], v[62:63]
	s_cbranch_vccnz .LBB0_124
	s_mov_b64 s[36:37], 0
	global_store_dwordx4 v[66:67], v[58:61], off offset:64

; DEVI float lo2f(unsigned u) { return __uint_as_float(u << 16); }
; DEVI float hi2f(unsigned u) { return __uint_as_float(u & 0xffff0000u); }
; DEVI void phase_resid_gemm(const Params& p, const bfu* A, int lda, int nkt, const bfu* wT, int ldb, const float* resid32,
;                            float* ssq_out, float* out32, char* lds) {
;     ...
;       for (int ni = 0; ni < 4; ++ni) {
;         const int n = n0 + wn * 64 + ni * 16 + fq * 4;
;         float4 r;
;         if (resid32) r = *(const float4*)(resid32 + (long)m * 1024 + n);
;         else { const uint2 u = *(const uint2*)(xs + (long)m * LDX + n); r = make_float4(lo2f(u.x), hi2f(u.x), lo2f(u.y), hi2f(u.y)); }
;         float4 o;
;         o.x = r.x + acc[ni][mi][0]; o.y = r.y + acc[ni][mi][1]; o.z = r.z + acc[ni][mi][2]; o.w = r.w + acc[ni][mi][3];
;         if (out32) *(float4*)(out32 + (long)m * 1024 + n) = o;
.LBB0_126:
	v_lshl_add_u64 v[218:219], v[70:71], 0, v[254:255]
	global_load_dwordx4 v[214:217], v[218:219], off offset:64
	s_and_b64 vcc, exec, s[42:43]
	s_mov_b64 s[36:37], -1
	s_waitcnt vmcnt(0)
	v_permlane16_swap_b32_e32 v214, v216
	v_permlane16_swap_b32_e32 v215, v217
	s_nop 1
	v_lshlrev_b32_e32 v60, 16, v214
	v_and_b32_e32 v61, 0xffff0000, v214
	v_lshlrev_b32_e32 v58, 16, v215
	v_and_b32_e32 v59, 0xffff0000, v215
	v_pk_add_f32 v[54:55], v[54:55], v[60:61]
	v_pk_add_f32 v[56:57], v[56:57], v[58:59]
	s_cbranch_vccnz .LBB0_128
	s_mov_b64 s[36:37], 0
	global_store_dwordx4 v[66:67], v[54:57], off offset:128

; DEVI float lo2f(unsigned u) { return __uint_as_float(u << 16); }
; DEVI float hi2f(unsigned u) { return __uint_as_float(u & 0xffff0000u); }
; DEVI void phase_resid_gemm(const Params& p, const bfu* A, int lda, int nkt, const bfu* wT, int ldb, const float* resid32,
;                            float* ssq_out, float* out32, char* lds) {
;     ...
;       for (int ni = 0; ni < 4; ++ni) {
;         const int n = n0 + wn * 64 + ni * 16 + fq * 4;
;         float4 r;
;         if (resid32) r = *(const float4*)(resid32 + (long)m * 1024 + n);
;         else { const uint2 u = *(const uint2*)(xs + (long)m * LDX + n); r = make_float4(lo2f(u.x), hi2f(u.x), lo2f(u.y), hi2f(u.y)); }
;         float4 o;
;         o.x = r.x + acc[ni][mi][0]; o.y = r.y + acc[ni][mi][1]; o.z = r.z + acc[ni][mi][2]; o.w = r.w + acc[ni][mi][3];
;         if (out32) *(float4*)(out32 + (long)m * 1024 + n) = o;
.LBB0_130:
	s_and_b64 vcc, exec, s[42:43]
	s_mov_b64 s[36:37], -1
	s_waitcnt vmcnt(0)
	v_lshlrev_b32_e32 v56, 16, v216
	v_and_b32_e32 v57, 0xffff0000, v216
	v_lshlrev_b32_e32 v54, 16, v217
	v_and_b32_e32 v55, 0xffff0000, v217
	v_pk_add_f32 v[46:47], v[46:47], v[56:57]
	v_pk_add_f32 v[48:49], v[48:49], v[54:55]
	s_cbranch_vccz .LBB0_133
	s_andn2_b64 vcc, exec, s[36:37]
	s_cbranch_vccz .LBB0_134

; DEVI float lo2f(unsigned u) { return __uint_as_float(u << 16); }
; DEVI float hi2f(unsigned u) { return __uint_as_float(u & 0xffff0000u); }
; DEVI void phase_resid_gemm(const Params& p, const bfu* A, int lda, int nkt, const bfu* wT, int ldb, const float* resid32,
;                            float* ssq_out, float* out32, char* lds) {
;     ...
;       const int m = m0 + wm * 128 + mi * 16 + fr;
;       float ss = 0.f;
; #pragma unroll
;       for (int ni = 0; ni < 4; ++ni) {
;         const int n = n0 + wn * 64 + ni * 16 + fq * 4;
;         float4 r;
;         if (resid32) r = *(const float4*)(resid32 + (long)m * 1024 + n);
;         else { const uint2 u = *(const uint2*)(xs + (long)m * LDX + n); r = make_float4(lo2f(u.x), hi2f(u.x), lo2f(u.y), hi2f(u.y)); }
;         float4 o;
;         o.x = r.x + acc[ni][mi][0]; o.y = r.y + acc[ni][mi][1]; o.z = r.z + acc[ni][mi][2]; o.w = r.w + acc[ni][mi][3];
;         if (out32) *(float4*)(out32 + (long)m * 1024 + n) = o;
.LBB0_138:
	s_waitcnt lgkmcnt(0)
	v_or_b32_e32 v46, 0x50, v132
	v_mov_b64_e32 v[48:49], s[2:3]
	v_mad_i64_i32 v[48:49], s[28:29], v46, s95, v[48:49]
	v_lshl_add_u64 v[54:55], v[130:131], 1, v[48:49]
	v_lshl_add_u64 v[218:219], v[54:55], 0, v[254:255]
	global_load_dwordx4 v[214:217], v[218:219], off
	v_ashrrev_i32_e32 v47, 31, v46
	v_lshlrev_b64 v[46:47], 12, v[46:47]
	v_lshl_add_u64 v[56:57], s[0:1], 0, v[46:47]
	s_mov_b64 s[36:37], -1
	s_and_b64 vcc, exec, s[42:43]
	s_waitcnt vmcnt(0)
	v_permlane16_swap_b32_e32 v214, v216
	v_permlane16_swap_b32_e32 v215, v217
	s_nop 1
	v_lshlrev_b32_e32 v46, 16, v214
	v_and_b32_e32 v47, 0xffff0000, v214
	v_lshlrev_b32_e32 v48, 16, v215
	v_and_b32_e32 v49, 0xffff0000, v215
	v_pk_add_f32 v[46:47], v[50:51], v[46:47]
	v_pk_add_f32 v[48:49], v[52:53], v[48:49]
	v_lshl_add_u64 v[50:51], v[130:131], 2, v[56:57]
	s_cbranch_vccnz .LBB0_140
	s_mov_b64 s[36:37], 0
	global_store_dwordx4 v[50:51], v[46:49], off

; DEVI float lo2f(unsigned u) { return __uint_as_float(u << 16); }
; DEVI float hi2f(unsigned u) { return __uint_as_float(u & 0xffff0000u); }
; DEVI void phase_resid_gemm(const Params& p, const bfu* A, int lda, int nkt, const bfu* wT, int ldb, const float* resid32,
;                            float* ssq_out, float* out32, char* lds) {
;     ...
;       for (int ni = 0; ni < 4; ++ni) {
;         const int n = n0 + wn * 64 + ni * 16 + fq * 4;
;         float4 r;
;         if (resid32) r = *(const float4*)(resid32 + (long)m * 1024 + n);
;         else { const uint2 u = *(const uint2*)(xs + (long)m * LDX + n); r = make_float4(lo2f(u.x), hi2f(u.x), lo2f(u.y), hi2f(u.y)); }
;         float4 o;
;         o.x = r.x + acc[ni][mi][0]; o.y = r.y + acc[ni][mi][1]; o.z = r.z + acc[ni][mi][2]; o.w = r.w + acc[ni][mi][3];
;         if (out32) *(float4*)(out32 + (long)m * 1024 + n) = o;
.LBB0_142:
	s_and_b64 vcc, exec, s[42:43]
	s_mov_b64 s[36:37], -1
	s_waitcnt vmcnt(0)
	v_lshlrev_b32_e32 v48, 16, v216
	v_and_b32_e32 v49, 0xffff0000, v216
	v_lshlrev_b32_e32 v46, 16, v217
	v_and_b32_e32 v47, 0xffff0000, v217
	v_pk_add_f32 v[42:43], v[42:43], v[48:49]
	v_pk_add_f32 v[44:45], v[44:45], v[46:47]
	s_cbranch_vccnz .LBB0_144
	s_mov_b64 s[36:37], 0
	global_store_dwordx4 v[50:51], v[42:45], off offset:64

; DEVI float lo2f(unsigned u) { return __uint_as_float(u << 16); }
; DEVI float hi2f(unsigned u) { return __uint_as_float(u & 0xffff0000u); }
; DEVI void phase_resid_gemm(const Params& p, const bfu* A, int lda, int nkt, const bfu* wT, int ldb, const float* resid32,
;                            float* ssq_out, float* out32, char* lds) {
;     ...
;       for (int ni = 0; ni < 4; ++ni) {
;         const int n = n0 + wn * 64 + ni * 16 + fq * 4;
;         float4 r;
;         if (resid32) r = *(const float4*)(resid32 + (long)m * 1024 + n);
;         else { const uint2 u = *(const uint2*)(xs + (long)m * LDX + n); r = make_float4(lo2f(u.x), hi2f(u.x), lo2f(u.y), hi2f(u.y)); }
;         float4 o;
;         o.x = r.x + acc[ni][mi][0]; o.y = r.y + acc[ni][mi][1]; o.z = r.z + acc[ni][mi][2]; o.w = r.w + acc[ni][mi][3];
;         if (out32) *(float4*)(out32 + (long)m * 1024 + n) = o;
.LBB0_146:
	v_lshl_add_u64 v[218:219], v[54:55], 0, v[254:255]
	global_load_dwordx4 v[214:217], v[218:219], off offset:64
	s_and_b64 vcc, exec, s[42:43]
	s_mov_b64 s[36:37], -1
	s_waitcnt vmcnt(0)
	v_permlane16_swap_b32_e32 v214, v216
	v_permlane16_swap_b32_e32 v215, v217
	s_nop 1
	v_lshlrev_b32_e32 v44, 16, v214
	v_and_b32_e32 v45, 0xffff0000, v214
	v_lshlrev_b32_e32 v42, 16, v215
	v_and_b32_e32 v43, 0xffff0000, v215
	v_pk_add_f32 v[38:39], v[38:39], v[44:45]
	v_pk_add_f32 v[40:41], v[40:41], v[42:43]
	s_cbranch_vccnz .LBB0_148
	s_mov_b64 s[36:37], 0
	global_store_dwordx4 v[50:51], v[38:41], off offset:128

; DEVI float lo2f(unsigned u) { return __uint_as_float(u << 16); }
; DEVI float hi2f(unsigned u) { return __uint_as_float(u & 0xffff0000u); }
; DEVI void phase_resid_gemm(const Params& p, const bfu* A, int lda, int nkt, const bfu* wT, int ldb, const float* resid32,
;                            float* ssq_out, float* out32, char* lds) {
;     ...
;       for (int ni = 0; ni < 4; ++ni) {
;         const int n = n0 + wn * 64 + ni * 16 + fq * 4;
;         float4 r;
;         if (resid32) r = *(const float4*)(resid32 + (long)m * 1024 + n);
;         else { const uint2 u = *(const uint2*)(xs + (long)m * LDX + n); r = make_float4(lo2f(u.x), hi2f(u.x), lo2f(u.y), hi2f(u.y)); }
;         float4 o;
;         o.x = r.x + acc[ni][mi][0]; o.y = r.y + acc[ni][mi][1]; o.z = r.z + acc[ni][mi][2]; o.w = r.w + acc[ni][mi][3];
;         if (out32) *(float4*)(out32 + (long)m * 1024 + n) = o;
.LBB0_150:
	s_and_b64 vcc, exec, s[42:43]
	s_mov_b64 s[36:37], -1
	s_waitcnt vmcnt(0)
	v_lshlrev_b32_e32 v40, 16, v216
	v_and_b32_e32 v41, 0xffff0000, v216
	v_lshlrev_b32_e32 v38, 16, v217
	v_and_b32_e32 v39, 0xffff0000, v217
	v_pk_add_f32 v[30:31], v[30:31], v[40:41]
	v_pk_add_f32 v[32:33], v[32:33], v[38:39]
	s_cbranch_vccz .LBB0_153
	s_andn2_b64 vcc, exec, s[36:37]
	s_cbranch_vccz .LBB0_154

; DEVI float lo2f(unsigned u) { return __uint_as_float(u << 16); }
; DEVI float hi2f(unsigned u) { return __uint_as_float(u & 0xffff0000u); }
; DEVI void phase_resid_gemm(const Params& p, const bfu* A, int lda, int nkt, const bfu* wT, int ldb, const float* resid32,
;                            float* ssq_out, float* out32, char* lds) {
;     ...
;       const int m = m0 + wm * 128 + mi * 16 + fr;
;       float ss = 0.f;
; #pragma unroll
;       for (int ni = 0; ni < 4; ++ni) {
;         const int n = n0 + wn * 64 + ni * 16 + fq * 4;
;         float4 r;
;         if (resid32) r = *(const float4*)(resid32 + (long)m * 1024 + n);
;         else { const uint2 u = *(const uint2*)(xs + (long)m * LDX + n); r = make_float4(lo2f(u.x), hi2f(u.x), lo2f(u.y), hi2f(u.y)); }
;         float4 o;
;         o.x = r.x + acc[ni][mi][0]; o.y = r.y + acc[ni][mi][1]; o.z = r.z + acc[ni][mi][2]; o.w = r.w + acc[ni][mi][3];
;         if (out32) *(float4*)(out32 + (long)m * 1024 + n) = o;
.LBB0_158:
	s_waitcnt lgkmcnt(0)
	v_or_b32_e32 v30, 0x60, v132
	v_mov_b64_e32 v[32:33], s[2:3]
	v_mad_i64_i32 v[32:33], s[28:29], v30, s95, v[32:33]
	v_lshl_add_u64 v[38:39], v[130:131], 1, v[32:33]
	v_lshl_add_u64 v[218:219], v[38:39], 0, v[254:255]
	global_load_dwordx4 v[214:217], v[218:219], off
	v_ashrrev_i32_e32 v31, 31, v30
	v_lshlrev_b64 v[30:31], 12, v[30:31]
	v_lshl_add_u64 v[40:41], s[0:1], 0, v[30:31]
	s_mov_b64 s[36:37], -1
	s_and_b64 vcc, exec, s[42:43]
	s_waitcnt vmcnt(0)
	v_permlane16_swap_b32_e32 v214, v216
	v_permlane16_swap_b32_e32 v215, v217
	s_nop 1
	v_lshlrev_b32_e32 v30, 16, v214
	v_and_b32_e32 v31, 0xffff0000, v214
	v_lshlrev_b32_e32 v32, 16, v215
	v_and_b32_e32 v33, 0xffff0000, v215
	v_pk_add_f32 v[30:31], v[34:35], v[30:31]
	v_pk_add_f32 v[32:33], v[36:37], v[32:33]
	v_lshl_add_u64 v[34:35], v[130:131], 2, v[40:41]
	s_cbranch_vccnz .LBB0_160
	s_mov_b64 s[36:37], 0
	global_store_dwordx4 v[34:35], v[30:33], off

; DEVI float lo2f(unsigned u) { return __uint_as_float(u << 16); }
; DEVI float hi2f(unsigned u) { return __uint_as_float(u & 0xffff0000u); }
; DEVI void phase_resid_gemm(const Params& p, const bfu* A, int lda, int nkt, const bfu* wT, int ldb, const float* resid32,
;                            float* ssq_out, float* out32, char* lds) {
;     ...
;       for (int ni = 0; ni < 4; ++ni) {
;         const int n = n0 + wn * 64 + ni * 16 + fq * 4;
;         float4 r;
;         if (resid32) r = *(const float4*)(resid32 + (long)m * 1024 + n);
;         else { const uint2 u = *(const uint2*)(xs + (long)m * LDX + n); r = make_float4(lo2f(u.x), hi2f(u.x), lo2f(u.y), hi2f(u.y)); }
;         float4 o;
;         o.x = r.x + acc[ni][mi][0]; o.y = r.y + acc[ni][mi][1]; o.z = r.z + acc[ni][mi][2]; o.w = r.w + acc[ni][mi][3];
;         if (out32) *(float4*)(out32 + (long)m * 1024 + n) = o;
.LBB0_162:
	s_and_b64 vcc, exec, s[42:43]
	s_mov_b64 s[36:37], -1
	s_waitcnt vmcnt(0)
	v_lshlrev_b32_e32 v32, 16, v216
	v_and_b32_e32 v33, 0xffff0000, v216
	v_lshlrev_b32_e32 v30, 16, v217
	v_and_b32_e32 v31, 0xffff0000, v217
	v_pk_add_f32 v[26:27], v[26:27], v[32:33]
	v_pk_add_f32 v[28:29], v[28:29], v[30:31]
	s_cbranch_vccnz .LBB0_164
	s_mov_b64 s[36:37], 0
	global_store_dwordx4 v[34:35], v[26:29], off offset:64

; DEVI float lo2f(unsigned u) { return __uint_as_float(u << 16); }
; DEVI float hi2f(unsigned u) { return __uint_as_float(u & 0xffff0000u); }
; DEVI void phase_resid_gemm(const Params& p, const bfu* A, int lda, int nkt, const bfu* wT, int ldb, const float* resid32,
;                            float* ssq_out, float* out32, char* lds) {
;     ...
;       for (int ni = 0; ni < 4; ++ni) {
;         const int n = n0 + wn * 64 + ni * 16 + fq * 4;
;         float4 r;
;         if (resid32) r = *(const float4*)(resid32 + (long)m * 1024 + n);
;         else { const uint2 u = *(const uint2*)(xs + (long)m * LDX + n); r = make_float4(lo2f(u.x), hi2f(u.x), lo2f(u.y), hi2f(u.y)); }
;         float4 o;
;         o.x = r.x + acc[ni][mi][0]; o.y = r.y + acc[ni][mi][1]; o.z = r.z + acc[ni][mi][2]; o.w = r.w + acc[ni][mi][3];
;         if (out32) *(float4*)(out32 + (long)m * 1024 + n) = o;
.LBB0_166:
	v_lshl_add_u64 v[218:219], v[38:39], 0, v[254:255]
	global_load_dwordx4 v[214:217], v[218:219], off offset:64
	s_and_b64 vcc, exec, s[42:43]
	s_mov_b64 s[36:37], -1
	s_waitcnt vmcnt(0)
	v_permlane16_swap_b32_e32 v214, v216
	v_permlane16_swap_b32_e32 v215, v217
	s_nop 1
	v_lshlrev_b32_e32 v28, 16, v214
	v_and_b32_e32 v29, 0xffff0000, v214
	v_lshlrev_b32_e32 v26, 16, v215
	v_and_b32_e32 v27, 0xffff0000, v215
	v_pk_add_f32 v[22:23], v[22:23], v[28:29]
	v_pk_add_f32 v[24:25], v[24:25], v[26:27]
	s_cbranch_vccnz .LBB0_168
	s_mov_b64 s[36:37], 0
	global_store_dwordx4 v[34:35], v[22:25], off offset:128

; DEVI float lo2f(unsigned u) { return __uint_as_float(u << 16); }
; DEVI float hi2f(unsigned u) { return __uint_as_float(u & 0xffff0000u); }
; DEVI void phase_resid_gemm(const Params& p, const bfu* A, int lda, int nkt, const bfu* wT, int ldb, const float* resid32,
;                            float* ssq_out, float* out32, char* lds) {
;     ...
;       for (int ni = 0; ni < 4; ++ni) {
;         const int n = n0 + wn * 64 + ni * 16 + fq * 4;
;         float4 r;
;         if (resid32) r = *(const float4*)(resid32 + (long)m * 1024 + n);
;         else { const uint2 u = *(const uint2*)(xs + (long)m * LDX + n); r = make_float4(lo2f(u.x), hi2f(u.x), lo2f(u.y), hi2f(u.y)); }
;         float4 o;
;         o.x = r.x + acc[ni][mi][0]; o.y = r.y + acc[ni][mi][1]; o.z = r.z + acc[ni][mi][2]; o.w = r.w + acc[ni][mi][3];
;         if (out32) *(float4*)(out32 + (long)m * 1024 + n) = o;
.LBB0_170:
	s_and_b64 vcc, exec, s[42:43]
	s_mov_b64 s[36:37], -1
	s_waitcnt vmcnt(0)
	v_lshlrev_b32_e32 v24, 16, v216
	v_and_b32_e32 v25, 0xffff0000, v216
	v_lshlrev_b32_e32 v22, 16, v217
	v_and_b32_e32 v23, 0xffff0000, v217
	v_pk_add_f32 v[18:19], v[18:19], v[24:25]
	v_pk_add_f32 v[20:21], v[20:21], v[22:23]
	s_cbranch_vccz .LBB0_173
	s_andn2_b64 vcc, exec, s[36:37]
	s_cbranch_vccz .LBB0_174

; DEVI float lo2f(unsigned u) { return __uint_as_float(u << 16); }
; DEVI float hi2f(unsigned u) { return __uint_as_float(u & 0xffff0000u); }
; DEVI void phase_resid_gemm(const Params& p, const bfu* A, int lda, int nkt, const bfu* wT, int ldb, const float* resid32,
;                            float* ssq_out, float* out32, char* lds) {
;     ...
;       const int m = m0 + wm * 128 + mi * 16 + fr;
;       float ss = 0.f;
; #pragma unroll
;       for (int ni = 0; ni < 4; ++ni) {
;         const int n = n0 + wn * 64 + ni * 16 + fq * 4;
;         float4 r;
;         if (resid32) r = *(const float4*)(resid32 + (long)m * 1024 + n);
;         else { const uint2 u = *(const uint2*)(xs + (long)m * LDX + n); r = make_float4(lo2f(u.x), hi2f(u.x), lo2f(u.y), hi2f(u.y)); }
;         float4 o;
;         o.x = r.x + acc[ni][mi][0]; o.y = r.y + acc[ni][mi][1]; o.z = r.z + acc[ni][mi][2]; o.w = r.w + acc[ni][mi][3];
;         if (out32) *(float4*)(out32 + (long)m * 1024 + n) = o;
.LBB0_178:
	v_or_b32_e32 v20, 0x70, v132
	s_waitcnt lgkmcnt(0)
	v_mov_b64_e32 v[18:19], s[2:3]
	v_mad_i64_i32 v[18:19], s[28:29], v20, s95, v[18:19]
	v_lshl_add_u64 v[18:19], v[130:131], 1, v[18:19]
	v_lshl_add_u64 v[218:219], v[18:19], 0, v[254:255]
	global_load_dwordx4 v[214:217], v[218:219], off
	v_ashrrev_i32_e32 v21, 31, v20
	v_lshlrev_b64 v[20:21], 12, v[20:21]
	v_lshl_add_u64 v[20:21], s[0:1], 0, v[20:21]
	s_mov_b64 s[36:37], -1
	s_and_b64 vcc, exec, s[42:43]
	v_lshl_add_u64 v[20:21], v[130:131], 2, v[20:21]
	s_waitcnt vmcnt(0)
	v_permlane16_swap_b32_e32 v214, v216
	v_permlane16_swap_b32_e32 v215, v217
	s_nop 1
	v_lshlrev_b32_e32 v24, 16, v214
	v_and_b32_e32 v25, 0xffff0000, v214
	v_lshlrev_b32_e32 v22, 16, v215
	v_and_b32_e32 v23, 0xffff0000, v215
	v_pk_add_f32 v[14:15], v[14:15], v[24:25]
	v_pk_add_f32 v[16:17], v[16:17], v[22:23]
	s_cbranch_vccnz .LBB0_180
	s_mov_b64 s[36:37], 0
	global_store_dwordx4 v[20:21], v[14:17], off

; DEVI float lo2f(unsigned u) { return __uint_as_float(u << 16); }
; DEVI float hi2f(unsigned u) { return __uint_as_float(u & 0xffff0000u); }
; DEVI void phase_resid_gemm(const Params& p, const bfu* A, int lda, int nkt, const bfu* wT, int ldb, const float* resid32,
;                            float* ssq_out, float* out32, char* lds) {
;     ...
;       for (int ni = 0; ni < 4; ++ni) {
;         const int n = n0 + wn * 64 + ni * 16 + fq * 4;
;         float4 r;
;         if (resid32) r = *(const float4*)(resid32 + (long)m * 1024 + n);
;         else { const uint2 u = *(const uint2*)(xs + (long)m * LDX + n); r = make_float4(lo2f(u.x), hi2f(u.x), lo2f(u.y), hi2f(u.y)); }
;         float4 o;
;         o.x = r.x + acc[ni][mi][0]; o.y = r.y + acc[ni][mi][1]; o.z = r.z + acc[ni][mi][2]; o.w = r.w + acc[ni][mi][3];
;         if (out32) *(float4*)(out32 + (long)m * 1024 + n) = o;
.LBB0_182:
	s_and_b64 vcc, exec, s[42:43]
	s_mov_b64 s[36:37], -1
	s_waitcnt vmcnt(0)
	v_lshlrev_b32_e32 v16, 16, v216
	v_and_b32_e32 v17, 0xffff0000, v216
	v_lshlrev_b32_e32 v14, 16, v217
	v_and_b32_e32 v15, 0xffff0000, v217
	v_pk_add_f32 v[10:11], v[10:11], v[16:17]
	v_pk_add_f32 v[12:13], v[12:13], v[14:15]
	s_cbranch_vccnz .LBB0_184
	s_mov_b64 s[36:37], 0
	global_store_dwordx4 v[20:21], v[10:13], off offset:64

; DEVI float lo2f(unsigned u) { return __uint_as_float(u << 16); }
; DEVI float hi2f(unsigned u) { return __uint_as_float(u & 0xffff0000u); }
; DEVI void phase_resid_gemm(const Params& p, const bfu* A, int lda, int nkt, const bfu* wT, int ldb, const float* resid32,
;                            float* ssq_out, float* out32, char* lds) {
;     ...
;       for (int ni = 0; ni < 4; ++ni) {
;         const int n = n0 + wn * 64 + ni * 16 + fq * 4;
;         float4 r;
;         if (resid32) r = *(const float4*)(resid32 + (long)m * 1024 + n);
;         else { const uint2 u = *(const uint2*)(xs + (long)m * LDX + n); r = make_float4(lo2f(u.x), hi2f(u.x), lo2f(u.y), hi2f(u.y)); }
;         float4 o;
;         o.x = r.x + acc[ni][mi][0]; o.y = r.y + acc[ni][mi][1]; o.z = r.z + acc[ni][mi][2]; o.w = r.w + acc[ni][mi][3];
;         if (out32) *(float4*)(out32 + (long)m * 1024 + n) = o;
.LBB0_186:
	v_lshl_add_u64 v[218:219], v[18:19], 0, v[254:255]
	global_load_dwordx4 v[214:217], v[218:219], off offset:64
	s_and_b64 vcc, exec, s[42:43]
	s_mov_b64 s[36:37], -1
	s_waitcnt vmcnt(0)
	v_permlane16_swap_b32_e32 v214, v216
	v_permlane16_swap_b32_e32 v215, v217
	s_nop 1
	v_lshlrev_b32_e32 v12, 16, v214
	v_and_b32_e32 v13, 0xffff0000, v214
	v_lshlrev_b32_e32 v10, 16, v215
	v_and_b32_e32 v11, 0xffff0000, v215
	v_pk_add_f32 v[6:7], v[6:7], v[12:13]
	v_pk_add_f32 v[8:9], v[8:9], v[10:11]
	s_cbranch_vccnz .LBB0_188
	s_mov_b64 s[36:37], 0
	global_store_dwordx4 v[20:21], v[6:9], off offset:128

; DEVI float lo2f(unsigned u) { return __uint_as_float(u << 16); }
; DEVI float hi2f(unsigned u) { return __uint_as_float(u & 0xffff0000u); }
; DEVI void phase_resid_gemm(const Params& p, const bfu* A, int lda, int nkt, const bfu* wT, int ldb, const float* resid32,
;                            float* ssq_out, float* out32, char* lds) {
;     ...
;       for (int ni = 0; ni < 4; ++ni) {
;         const int n = n0 + wn * 64 + ni * 16 + fq * 4;
;         float4 r;
;         if (resid32) r = *(const float4*)(resid32 + (long)m * 1024 + n);
;         else { const uint2 u = *(const uint2*)(xs + (long)m * LDX + n); r = make_float4(lo2f(u.x), hi2f(u.x), lo2f(u.y), hi2f(u.y)); }
;         float4 o;
;         o.x = r.x + acc[ni][mi][0]; o.y = r.y + acc[ni][mi][1]; o.z = r.z + acc[ni][mi][2]; o.w = r.w + acc[ni][mi][3];
;         if (out32) *(float4*)(out32 + (long)m * 1024 + n) = o;
.LBB0_190:
	s_and_b64 vcc, exec, s[42:43]
	s_mov_b64 s[36:37], -1
	s_waitcnt vmcnt(0)
	v_lshlrev_b32_e32 v8, 16, v216
	v_and_b32_e32 v9, 0xffff0000, v216
	v_lshlrev_b32_e32 v6, 16, v217
	v_and_b32_e32 v7, 0xffff0000, v217
	v_pk_add_f32 v[2:3], v[2:3], v[8:9]
	v_pk_add_f32 v[4:5], v[4:5], v[6:7]
	s_cbranch_vccz .LBB0_193
	s_andn2_b64 vcc, exec, s[36:37]
	s_cbranch_vccz .LBB0_194

; DEVI float lo2f(unsigned u) { return __uint_as_float(u << 16); }
; DEVI float hi2f(unsigned u) { return __uint_as_float(u & 0xffff0000u); }
; DEVI void phase_resid_gemm(const Params& p, const bfu* A, int lda, int nkt, const bfu* wT, int ldb, const float* resid32,
;                            float* ssq_out, float* out32, char* lds) {
;     ...
;       for (int ni = 0; ni < 4; ++ni) {
;         const int n = n0 + wn * 64 + ni * 16 + fq * 4;
;         float4 r;
;         if (resid32) r = *(const float4*)(resid32 + (long)m * 1024 + n);
;         else { const uint2 u = *(const uint2*)(xs + (long)m * LDX + n); r = make_float4(lo2f(u.x), hi2f(u.x), lo2f(u.y), hi2f(u.y)); }
;         float4 o;
;         o.x = r.x + acc[ni][mi][0]; o.y = r.y + acc[ni][mi][1]; o.z = r.z + acc[ni][mi][2]; o.w = r.w + acc[ni][mi][3];
.LBB0_248:
	v_mov_b64_e32 v[134:135], s[2:3]
	v_mad_i64_i32 v[134:135], s[28:29], v132, s95, v[134:135]
	s_andn2_b64 vcc, exec, s[36:37]
	v_lshl_add_u64 v[134:135], v[130:131], 1, v[134:135]
	s_cbranch_vccnz .LBB0_250
	v_lshl_add_u64 v[218:219], v[134:135], 0, v[254:255]
	global_load_dwordx4 v[214:217], v[218:219], off
	s_waitcnt vmcnt(0)
	v_permlane16_swap_b32_e32 v214, v216
	v_permlane16_swap_b32_e32 v215, v217
	s_nop 1
	v_lshlrev_b32_e32 v126, 16, v214
	v_and_b32_e32 v127, 0xffff0000, v214
	v_lshlrev_b32_e32 v128, 16, v215
	v_and_b32_e32 v129, 0xffff0000, v215

; DEVI float lo2f(unsigned u) { return __uint_as_float(u << 16); }
; DEVI float hi2f(unsigned u) { return __uint_as_float(u & 0xffff0000u); }
; DEVI void phase_resid_gemm(const Params& p, const bfu* A, int lda, int nkt, const bfu* wT, int ldb, const float* resid32,
;                            float* ssq_out, float* out32, char* lds) {
;     ...
;       for (int ni = 0; ni < 4; ++ni) {
;         const int n = n0 + wn * 64 + ni * 16 + fq * 4;
;         float4 r;
;         if (resid32) r = *(const float4*)(resid32 + (long)m * 1024 + n);
;         else { const uint2 u = *(const uint2*)(xs + (long)m * LDX + n); r = make_float4(lo2f(u.x), hi2f(u.x), lo2f(u.y), hi2f(u.y)); }
;         float4 o;
;         o.x = r.x + acc[ni][mi][0]; o.y = r.y + acc[ni][mi][1]; o.z = r.z + acc[ni][mi][2]; o.w = r.w + acc[ni][mi][3];
.LBB0_252:
	s_waitcnt vmcnt(0)
	v_lshlrev_b32_e32 v126, 16, v216
	v_and_b32_e32 v127, 0xffff0000, v216
	v_lshlrev_b32_e32 v128, 16, v217
	v_and_b32_e32 v129, 0xffff0000, v217

; DEVI float lo2f(unsigned u) { return __uint_as_float(u << 16); }
; DEVI float hi2f(unsigned u) { return __uint_as_float(u & 0xffff0000u); }
; DEVI void phase_resid_gemm(const Params& p, const bfu* A, int lda, int nkt, const bfu* wT, int ldb, const float* resid32,
;                            float* ssq_out, float* out32, char* lds) {
;     ...
;       for (int ni = 0; ni < 4; ++ni) {
;         const int n = n0 + wn * 64 + ni * 16 + fq * 4;
;         float4 r;
;         if (resid32) r = *(const float4*)(resid32 + (long)m * 1024 + n);
;         else { const uint2 u = *(const uint2*)(xs + (long)m * LDX + n); r = make_float4(lo2f(u.x), hi2f(u.x), lo2f(u.y), hi2f(u.y)); }
;         float4 o;
;         o.x = r.x + acc[ni][mi][0]; o.y = r.y + acc[ni][mi][1]; o.z = r.z + acc[ni][mi][2]; o.w = r.w + acc[ni][mi][3];
.LBB0_255:
	v_lshl_add_u64 v[218:219], v[134:135], 0, v[254:255]
	global_load_dwordx4 v[214:217], v[218:219], off offset:64
	s_waitcnt vmcnt(0)
	v_permlane16_swap_b32_e32 v214, v216
	v_permlane16_swap_b32_e32 v215, v217
	s_nop 1
	v_lshlrev_b32_e32 v122, 16, v214
	v_and_b32_e32 v123, 0xffff0000, v214
	v_lshlrev_b32_e32 v124, 16, v215
	v_and_b32_e32 v125, 0xffff0000, v215

; DEVI float lo2f(unsigned u) { return __uint_as_float(u << 16); }
; DEVI float hi2f(unsigned u) { return __uint_as_float(u & 0xffff0000u); }
; DEVI void phase_resid_gemm(const Params& p, const bfu* A, int lda, int nkt, const bfu* wT, int ldb, const float* resid32,
;                            float* ssq_out, float* out32, char* lds) {
;     ...
;       for (int ni = 0; ni < 4; ++ni) {
;         const int n = n0 + wn * 64 + ni * 16 + fq * 4;
;         float4 r;
;         if (resid32) r = *(const float4*)(resid32 + (long)m * 1024 + n);
;         else { const uint2 u = *(const uint2*)(xs + (long)m * LDX + n); r = make_float4(lo2f(u.x), hi2f(u.x), lo2f(u.y), hi2f(u.y)); }
;         float4 o;
;         o.x = r.x + acc[ni][mi][0]; o.y = r.y + acc[ni][mi][1]; o.z = r.z + acc[ni][mi][2]; o.w = r.w + acc[ni][mi][3];
.LBB0_258:
	s_waitcnt vmcnt(0)
	v_lshlrev_b32_e32 v118, 16, v216
	v_and_b32_e32 v119, 0xffff0000, v216
	v_lshlrev_b32_e32 v120, 16, v217
	v_and_b32_e32 v121, 0xffff0000, v217

; DEVI float lo2f(unsigned u) { return __uint_as_float(u << 16); }
; DEVI float hi2f(unsigned u) { return __uint_as_float(u & 0xffff0000u); }
; DEVI void phase_resid_gemm(const Params& p, const bfu* A, int lda, int nkt, const bfu* wT, int ldb, const float* resid32,
;                            float* ssq_out, float* out32, char* lds) {
;     ...
;       for (int ni = 0; ni < 4; ++ni) {
;         const int n = n0 + wn * 64 + ni * 16 + fq * 4;
;         float4 r;
;         if (resid32) r = *(const float4*)(resid32 + (long)m * 1024 + n);
;         else { const uint2 u = *(const uint2*)(xs + (long)m * LDX + n); r = make_float4(lo2f(u.x), hi2f(u.x), lo2f(u.y), hi2f(u.y)); }
;         float4 o;
;         o.x = r.x + acc[ni][mi][0]; o.y = r.y + acc[ni][mi][1]; o.z = r.z + acc[ni][mi][2]; o.w = r.w + acc[ni][mi][3];
.LBB0_267:
	v_mov_b64_e32 v[124:125], s[2:3]
	v_mad_i64_i32 v[118:119], s[28:29], v118, s95, v[124:125]
	s_andn2_b64 vcc, exec, s[36:37]
	v_lshl_add_u64 v[118:119], v[130:131], 1, v[118:119]
	s_cbranch_vccnz .LBB0_269
	v_lshl_add_u64 v[218:219], v[118:119], 0, v[254:255]
	global_load_dwordx4 v[214:217], v[218:219], off
	s_waitcnt vmcnt(0)
	v_permlane16_swap_b32_e32 v214, v216
	v_permlane16_swap_b32_e32 v215, v217
	s_nop 1
	v_lshlrev_b32_e32 v110, 16, v214
	v_and_b32_e32 v111, 0xffff0000, v214
	v_lshlrev_b32_e32 v112, 16, v215
	v_and_b32_e32 v113, 0xffff0000, v215

; DEVI float lo2f(unsigned u) { return __uint_as_float(u << 16); }
; DEVI float hi2f(unsigned u) { return __uint_as_float(u & 0xffff0000u); }
; DEVI void phase_resid_gemm(const Params& p, const bfu* A, int lda, int nkt, const bfu* wT, int ldb, const float* resid32,
;                            float* ssq_out, float* out32, char* lds) {
;     ...
;       for (int ni = 0; ni < 4; ++ni) {
;         const int n = n0 + wn * 64 + ni * 16 + fq * 4;
;         float4 r;
;         if (resid32) r = *(const float4*)(resid32 + (long)m * 1024 + n);
;         else { const uint2 u = *(const uint2*)(xs + (long)m * LDX + n); r = make_float4(lo2f(u.x), hi2f(u.x), lo2f(u.y), hi2f(u.y)); }
;         float4 o;
;         o.x = r.x + acc[ni][mi][0]; o.y = r.y + acc[ni][mi][1]; o.z = r.z + acc[ni][mi][2]; o.w = r.w + acc[ni][mi][3];
.LBB0_271:
	s_waitcnt vmcnt(0)
	v_lshlrev_b32_e32 v110, 16, v216
	v_and_b32_e32 v111, 0xffff0000, v216
	v_lshlrev_b32_e32 v112, 16, v217
	v_and_b32_e32 v113, 0xffff0000, v217

; DEVI float lo2f(unsigned u) { return __uint_as_float(u << 16); }
; DEVI float hi2f(unsigned u) { return __uint_as_float(u & 0xffff0000u); }
; DEVI void phase_resid_gemm(const Params& p, const bfu* A, int lda, int nkt, const bfu* wT, int ldb, const float* resid32,
;                            float* ssq_out, float* out32, char* lds) {
;     ...
;       for (int ni = 0; ni < 4; ++ni) {
;         const int n = n0 + wn * 64 + ni * 16 + fq * 4;
;         float4 r;
;         if (resid32) r = *(const float4*)(resid32 + (long)m * 1024 + n);
;         else { const uint2 u = *(const uint2*)(xs + (long)m * LDX + n); r = make_float4(lo2f(u.x), hi2f(u.x), lo2f(u.y), hi2f(u.y)); }
;         float4 o;
;         o.x = r.x + acc[ni][mi][0]; o.y = r.y + acc[ni][mi][1]; o.z = r.z + acc[ni][mi][2]; o.w = r.w + acc[ni][mi][3];
.LBB0_274:
	v_lshl_add_u64 v[218:219], v[118:119], 0, v[254:255]
	global_load_dwordx4 v[214:217], v[218:219], off offset:64
	s_waitcnt vmcnt(0)
	v_permlane16_swap_b32_e32 v214, v216
	v_permlane16_swap_b32_e32 v215, v217
	s_nop 1
	v_lshlrev_b32_e32 v106, 16, v214
	v_and_b32_e32 v107, 0xffff0000, v214
	v_lshlrev_b32_e32 v108, 16, v215
	v_and_b32_e32 v109, 0xffff0000, v215

; DEVI float lo2f(unsigned u) { return __uint_as_float(u << 16); }
; DEVI float hi2f(unsigned u) { return __uint_as_float(u & 0xffff0000u); }
; DEVI void phase_resid_gemm(const Params& p, const bfu* A, int lda, int nkt, const bfu* wT, int ldb, const float* resid32,
;                            float* ssq_out, float* out32, char* lds) {
;     ...
;       for (int ni = 0; ni < 4; ++ni) {
;         const int n = n0 + wn * 64 + ni * 16 + fq * 4;
;         float4 r;
;         if (resid32) r = *(const float4*)(resid32 + (long)m * 1024 + n);
;         else { const uint2 u = *(const uint2*)(xs + (long)m * LDX + n); r = make_float4(lo2f(u.x), hi2f(u.x), lo2f(u.y), hi2f(u.y)); }
;         float4 o;
;         o.x = r.x + acc[ni][mi][0]; o.y = r.y + acc[ni][mi][1]; o.z = r.z + acc[ni][mi][2]; o.w = r.w + acc[ni][mi][3];
.LBB0_277:
	s_waitcnt vmcnt(0)
	v_lshlrev_b32_e32 v102, 16, v216
	v_and_b32_e32 v103, 0xffff0000, v216
	v_lshlrev_b32_e32 v104, 16, v217
	v_and_b32_e32 v105, 0xffff0000, v217

; DEVI float lo2f(unsigned u) { return __uint_as_float(u << 16); }
; DEVI float hi2f(unsigned u) { return __uint_as_float(u & 0xffff0000u); }
; DEVI void phase_resid_gemm(const Params& p, const bfu* A, int lda, int nkt, const bfu* wT, int ldb, const float* resid32,
;                            float* ssq_out, float* out32, char* lds) {
;     ...
;       for (int ni = 0; ni < 4; ++ni) {
;         const int n = n0 + wn * 64 + ni * 16 + fq * 4;
;         float4 r;
;         if (resid32) r = *(const float4*)(resid32 + (long)m * 1024 + n);
;         else { const uint2 u = *(const uint2*)(xs + (long)m * LDX + n); r = make_float4(lo2f(u.x), hi2f(u.x), lo2f(u.y), hi2f(u.y)); }
;         float4 o;
;         o.x = r.x + acc[ni][mi][0]; o.y = r.y + acc[ni][mi][1]; o.z = r.z + acc[ni][mi][2]; o.w = r.w + acc[ni][mi][3];
.LBB0_286:
	v_mov_b64_e32 v[106:107], s[2:3]
	v_mad_i64_i32 v[102:103], s[28:29], v102, s95, v[106:107]
	s_andn2_b64 vcc, exec, s[36:37]
	v_lshl_add_u64 v[102:103], v[130:131], 1, v[102:103]
	s_cbranch_vccnz .LBB0_288
	v_lshl_add_u64 v[218:219], v[102:103], 0, v[254:255]
	global_load_dwordx4 v[214:217], v[218:219], off
	s_waitcnt vmcnt(0)
	v_permlane16_swap_b32_e32 v214, v216
	v_permlane16_swap_b32_e32 v215, v217
	s_nop 1
	v_lshlrev_b32_e32 v94, 16, v214
	v_and_b32_e32 v95, 0xffff0000, v214
	v_lshlrev_b32_e32 v96, 16, v215
	v_and_b32_e32 v97, 0xffff0000, v215

; DEVI float lo2f(unsigned u) { return __uint_as_float(u << 16); }
; DEVI float hi2f(unsigned u) { return __uint_as_float(u & 0xffff0000u); }
; DEVI void phase_resid_gemm(const Params& p, const bfu* A, int lda, int nkt, const bfu* wT, int ldb, const float* resid32,
;                            float* ssq_out, float* out32, char* lds) {
;     ...
;       for (int ni = 0; ni < 4; ++ni) {
;         const int n = n0 + wn * 64 + ni * 16 + fq * 4;
;         float4 r;
;         if (resid32) r = *(const float4*)(resid32 + (long)m * 1024 + n);
;         else { const uint2 u = *(const uint2*)(xs + (long)m * LDX + n); r = make_float4(lo2f(u.x), hi2f(u.x), lo2f(u.y), hi2f(u.y)); }
;         float4 o;
;         o.x = r.x + acc[ni][mi][0]; o.y = r.y + acc[ni][mi][1]; o.z = r.z + acc[ni][mi][2]; o.w = r.w + acc[ni][mi][3];
.LBB0_290:
	s_waitcnt vmcnt(0)
	v_lshlrev_b32_e32 v94, 16, v216
	v_and_b32_e32 v95, 0xffff0000, v216
	v_lshlrev_b32_e32 v96, 16, v217
	v_and_b32_e32 v97, 0xffff0000, v217

; DEVI float lo2f(unsigned u) { return __uint_as_float(u << 16); }
; DEVI float hi2f(unsigned u) { return __uint_as_float(u & 0xffff0000u); }
; DEVI void phase_resid_gemm(const Params& p, const bfu* A, int lda, int nkt, const bfu* wT, int ldb, const float* resid32,
;                            float* ssq_out, float* out32, char* lds) {
;     ...
;       for (int ni = 0; ni < 4; ++ni) {
;         const int n = n0 + wn * 64 + ni * 16 + fq * 4;
;         float4 r;
;         if (resid32) r = *(const float4*)(resid32 + (long)m * 1024 + n);
;         else { const uint2 u = *(const uint2*)(xs + (long)m * LDX + n); r = make_float4(lo2f(u.x), hi2f(u.x), lo2f(u.y), hi2f(u.y)); }
;         float4 o;
;         o.x = r.x + acc[ni][mi][0]; o.y = r.y + acc[ni][mi][1]; o.z = r.z + acc[ni][mi][2]; o.w = r.w + acc[ni][mi][3];
.LBB0_293:
	v_lshl_add_u64 v[218:219], v[102:103], 0, v[254:255]
	global_load_dwordx4 v[214:217], v[218:219], off offset:64
	s_waitcnt vmcnt(0)
	v_permlane16_swap_b32_e32 v214, v216
	v_permlane16_swap_b32_e32 v215, v217
	s_nop 1
	v_lshlrev_b32_e32 v90, 16, v214
	v_and_b32_e32 v91, 0xffff0000, v214
	v_lshlrev_b32_e32 v92, 16, v215
	v_and_b32_e32 v93, 0xffff0000, v215

; DEVI float lo2f(unsigned u) { return __uint_as_float(u << 16); }
; DEVI float hi2f(unsigned u) { return __uint_as_float(u & 0xffff0000u); }
; DEVI void phase_resid_gemm(const Params& p, const bfu* A, int lda, int nkt, const bfu* wT, int ldb, const float* resid32,
;                            float* ssq_out, float* out32, char* lds) {
;     ...
;       for (int ni = 0; ni < 4; ++ni) {
;         const int n = n0 + wn * 64 + ni * 16 + fq * 4;
;         float4 r;
;         if (resid32) r = *(const float4*)(resid32 + (long)m * 1024 + n);
;         else { const uint2 u = *(const uint2*)(xs + (long)m * LDX + n); r = make_float4(lo2f(u.x), hi2f(u.x), lo2f(u.y), hi2f(u.y)); }
;         float4 o;
;         o.x = r.x + acc[ni][mi][0]; o.y = r.y + acc[ni][mi][1]; o.z = r.z + acc[ni][mi][2]; o.w = r.w + acc[ni][mi][3];
.LBB0_296:
	s_waitcnt vmcnt(0)
	v_lshlrev_b32_e32 v86, 16, v216
	v_and_b32_e32 v87, 0xffff0000, v216
	v_lshlrev_b32_e32 v88, 16, v217
	v_and_b32_e32 v89, 0xffff0000, v217

; DEVI float lo2f(unsigned u) { return __uint_as_float(u << 16); }
; DEVI float hi2f(unsigned u) { return __uint_as_float(u & 0xffff0000u); }
; DEVI void phase_resid_gemm(const Params& p, const bfu* A, int lda, int nkt, const bfu* wT, int ldb, const float* resid32,
;                            float* ssq_out, float* out32, char* lds) {
;     ...
;       for (int ni = 0; ni < 4; ++ni) {
;         const int n = n0 + wn * 64 + ni * 16 + fq * 4;
;         float4 r;
;         if (resid32) r = *(const float4*)(resid32 + (long)m * 1024 + n);
;         else { const uint2 u = *(const uint2*)(xs + (long)m * LDX + n); r = make_float4(lo2f(u.x), hi2f(u.x), lo2f(u.y), hi2f(u.y)); }
;         float4 o;
;         o.x = r.x + acc[ni][mi][0]; o.y = r.y + acc[ni][mi][1]; o.z = r.z + acc[ni][mi][2]; o.w = r.w + acc[ni][mi][3];
.LBB0_305:
	v_mov_b64_e32 v[90:91], s[2:3]
	v_mad_i64_i32 v[86:87], s[28:29], v86, s95, v[90:91]
	s_andn2_b64 vcc, exec, s[36:37]
	v_lshl_add_u64 v[86:87], v[130:131], 1, v[86:87]
	s_cbranch_vccnz .LBB0_307
	v_lshl_add_u64 v[218:219], v[86:87], 0, v[254:255]
	global_load_dwordx4 v[214:217], v[218:219], off
	s_waitcnt vmcnt(0)
	v_permlane16_swap_b32_e32 v214, v216
	v_permlane16_swap_b32_e32 v215, v217
	s_nop 1
	v_lshlrev_b32_e32 v78, 16, v214
	v_and_b32_e32 v79, 0xffff0000, v214
	v_lshlrev_b32_e32 v80, 16, v215
	v_and_b32_e32 v81, 0xffff0000, v215

; DEVI float lo2f(unsigned u) { return __uint_as_float(u << 16); }
; DEVI float hi2f(unsigned u) { return __uint_as_float(u & 0xffff0000u); }
; DEVI void phase_resid_gemm(const Params& p, const bfu* A, int lda, int nkt, const bfu* wT, int ldb, const float* resid32,
;                            float* ssq_out, float* out32, char* lds) {
;     ...
;       for (int ni = 0; ni < 4; ++ni) {
;         const int n = n0 + wn * 64 + ni * 16 + fq * 4;
;         float4 r;
;         if (resid32) r = *(const float4*)(resid32 + (long)m * 1024 + n);
;         else { const uint2 u = *(const uint2*)(xs + (long)m * LDX + n); r = make_float4(lo2f(u.x), hi2f(u.x), lo2f(u.y), hi2f(u.y)); }
;         float4 o;
;         o.x = r.x + acc[ni][mi][0]; o.y = r.y + acc[ni][mi][1]; o.z = r.z + acc[ni][mi][2]; o.w = r.w + acc[ni][mi][3];
.LBB0_309:
	s_waitcnt vmcnt(0)
	v_lshlrev_b32_e32 v78, 16, v216
	v_and_b32_e32 v79, 0xffff0000, v216
	v_lshlrev_b32_e32 v80, 16, v217
	v_and_b32_e32 v81, 0xffff0000, v217

; DEVI float lo2f(unsigned u) { return __uint_as_float(u << 16); }
; DEVI float hi2f(unsigned u) { return __uint_as_float(u & 0xffff0000u); }
; DEVI void phase_resid_gemm(const Params& p, const bfu* A, int lda, int nkt, const bfu* wT, int ldb, const float* resid32,
;                            float* ssq_out, float* out32, char* lds) {
;     ...
;       for (int ni = 0; ni < 4; ++ni) {
;         const int n = n0 + wn * 64 + ni * 16 + fq * 4;
;         float4 r;
;         if (resid32) r = *(const float4*)(resid32 + (long)m * 1024 + n);
;         else { const uint2 u = *(const uint2*)(xs + (long)m * LDX + n); r = make_float4(lo2f(u.x), hi2f(u.x), lo2f(u.y), hi2f(u.y)); }
;         float4 o;
;         o.x = r.x + acc[ni][mi][0]; o.y = r.y + acc[ni][mi][1]; o.z = r.z + acc[ni][mi][2]; o.w = r.w + acc[ni][mi][3];
.LBB0_312:
	v_lshl_add_u64 v[218:219], v[86:87], 0, v[254:255]
	global_load_dwordx4 v[214:217], v[218:219], off offset:64
	s_waitcnt vmcnt(0)
	v_permlane16_swap_b32_e32 v214, v216
	v_permlane16_swap_b32_e32 v215, v217
	s_nop 1
	v_lshlrev_b32_e32 v74, 16, v214
	v_and_b32_e32 v75, 0xffff0000, v214
	v_lshlrev_b32_e32 v76, 16, v215
	v_and_b32_e32 v77, 0xffff0000, v215

; DEVI float lo2f(unsigned u) { return __uint_as_float(u << 16); }
; DEVI float hi2f(unsigned u) { return __uint_as_float(u & 0xffff0000u); }
; DEVI void phase_resid_gemm(const Params& p, const bfu* A, int lda, int nkt, const bfu* wT, int ldb, const float* resid32,
;                            float* ssq_out, float* out32, char* lds) {
;     ...
;       for (int ni = 0; ni < 4; ++ni) {
;         const int n = n0 + wn * 64 + ni * 16 + fq * 4;
;         float4 r;
;         if (resid32) r = *(const float4*)(resid32 + (long)m * 1024 + n);
;         else { const uint2 u = *(const uint2*)(xs + (long)m * LDX + n); r = make_float4(lo2f(u.x), hi2f(u.x), lo2f(u.y), hi2f(u.y)); }
;         float4 o;
;         o.x = r.x + acc[ni][mi][0]; o.y = r.y + acc[ni][mi][1]; o.z = r.z + acc[ni][mi][2]; o.w = r.w + acc[ni][mi][3];
.LBB0_315:
	s_waitcnt vmcnt(0)
	v_lshlrev_b32_e32 v70, 16, v216
	v_and_b32_e32 v71, 0xffff0000, v216
	v_lshlrev_b32_e32 v72, 16, v217
	v_and_b32_e32 v73, 0xffff0000, v217

; DEVI float lo2f(unsigned u) { return __uint_as_float(u << 16); }
; DEVI float hi2f(unsigned u) { return __uint_as_float(u & 0xffff0000u); }
; DEVI void phase_resid_gemm(const Params& p, const bfu* A, int lda, int nkt, const bfu* wT, int ldb, const float* resid32,
;                            float* ssq_out, float* out32, char* lds) {
;     ...
;       for (int ni = 0; ni < 4; ++ni) {
;         const int n = n0 + wn * 64 + ni * 16 + fq * 4;
;         float4 r;
;         if (resid32) r = *(const float4*)(resid32 + (long)m * 1024 + n);
;         else { const uint2 u = *(const uint2*)(xs + (long)m * LDX + n); r = make_float4(lo2f(u.x), hi2f(u.x), lo2f(u.y), hi2f(u.y)); }
;         float4 o;
;         o.x = r.x + acc[ni][mi][0]; o.y = r.y + acc[ni][mi][1]; o.z = r.z + acc[ni][mi][2]; o.w = r.w + acc[ni][mi][3];
.LBB0_324:
	v_mov_b64_e32 v[74:75], s[2:3]
	v_mad_i64_i32 v[70:71], s[28:29], v70, s95, v[74:75]
	s_andn2_b64 vcc, exec, s[36:37]
	v_lshl_add_u64 v[70:71], v[130:131], 1, v[70:71]
	s_cbranch_vccnz .LBB0_326
	v_lshl_add_u64 v[218:219], v[70:71], 0, v[254:255]
	global_load_dwordx4 v[214:217], v[218:219], off
	s_waitcnt vmcnt(0)
	v_permlane16_swap_b32_e32 v214, v216
	v_permlane16_swap_b32_e32 v215, v217
	s_nop 1
	v_lshlrev_b32_e32 v62, 16, v214
	v_and_b32_e32 v63, 0xffff0000, v214
	v_lshlrev_b32_e32 v64, 16, v215
	v_and_b32_e32 v65, 0xffff0000, v215

; DEVI float lo2f(unsigned u) { return __uint_as_float(u << 16); }
; DEVI float hi2f(unsigned u) { return __uint_as_float(u & 0xffff0000u); }
; DEVI void phase_resid_gemm(const Params& p, const bfu* A, int lda, int nkt, const bfu* wT, int ldb, const float* resid32,
;                            float* ssq_out, float* out32, char* lds) {
;     ...
;       for (int ni = 0; ni < 4; ++ni) {
;         const int n = n0 + wn * 64 + ni * 16 + fq * 4;
;         float4 r;
;         if (resid32) r = *(const float4*)(resid32 + (long)m * 1024 + n);
;         else { const uint2 u = *(const uint2*)(xs + (long)m * LDX + n); r = make_float4(lo2f(u.x), hi2f(u.x), lo2f(u.y), hi2f(u.y)); }
;         float4 o;
;         o.x = r.x + acc[ni][mi][0]; o.y = r.y + acc[ni][mi][1]; o.z = r.z + acc[ni][mi][2]; o.w = r.w + acc[ni][mi][3];
.LBB0_328:
	s_waitcnt vmcnt(0)
	v_lshlrev_b32_e32 v62, 16, v216
	v_and_b32_e32 v63, 0xffff0000, v216
	v_lshlrev_b32_e32 v64, 16, v217
	v_and_b32_e32 v65, 0xffff0000, v217

; DEVI float lo2f(unsigned u) { return __uint_as_float(u << 16); }
; DEVI float hi2f(unsigned u) { return __uint_as_float(u & 0xffff0000u); }
; DEVI void phase_resid_gemm(const Params& p, const bfu* A, int lda, int nkt, const bfu* wT, int ldb, const float* resid32,
;                            float* ssq_out, float* out32, char* lds) {
;     ...
;       for (int ni = 0; ni < 4; ++ni) {
;         const int n = n0 + wn * 64 + ni * 16 + fq * 4;
;         float4 r;
;         if (resid32) r = *(const float4*)(resid32 + (long)m * 1024 + n);
;         else { const uint2 u = *(const uint2*)(xs + (long)m * LDX + n); r = make_float4(lo2f(u.x), hi2f(u.x), lo2f(u.y), hi2f(u.y)); }
;         float4 o;
;         o.x = r.x + acc[ni][mi][0]; o.y = r.y + acc[ni][mi][1]; o.z = r.z + acc[ni][mi][2]; o.w = r.w + acc[ni][mi][3];
.LBB0_331:
	v_lshl_add_u64 v[218:219], v[70:71], 0, v[254:255]
	global_load_dwordx4 v[214:217], v[218:219], off offset:64
	s_waitcnt vmcnt(0)
	v_permlane16_swap_b32_e32 v214, v216
	v_permlane16_swap_b32_e32 v215, v217
	s_nop 1
	v_lshlrev_b32_e32 v58, 16, v214
	v_and_b32_e32 v59, 0xffff0000, v214
	v_lshlrev_b32_e32 v60, 16, v215
	v_and_b32_e32 v61, 0xffff0000, v215

; DEVI float lo2f(unsigned u) { return __uint_as_float(u << 16); }
; DEVI float hi2f(unsigned u) { return __uint_as_float(u & 0xffff0000u); }
; DEVI void phase_resid_gemm(const Params& p, const bfu* A, int lda, int nkt, const bfu* wT, int ldb, const float* resid32,
;                            float* ssq_out, float* out32, char* lds) {
;     ...
;       for (int ni = 0; ni < 4; ++ni) {
;         const int n = n0 + wn * 64 + ni * 16 + fq * 4;
;         float4 r;
;         if (resid32) r = *(const float4*)(resid32 + (long)m * 1024 + n);
;         else { const uint2 u = *(const uint2*)(xs + (long)m * LDX + n); r = make_float4(lo2f(u.x), hi2f(u.x), lo2f(u.y), hi2f(u.y)); }
;         float4 o;
;         o.x = r.x + acc[ni][mi][0]; o.y = r.y + acc[ni][mi][1]; o.z = r.z + acc[ni][mi][2]; o.w = r.w + acc[ni][mi][3];
.LBB0_334:
	s_waitcnt vmcnt(0)
	v_lshlrev_b32_e32 v54, 16, v216
	v_and_b32_e32 v55, 0xffff0000, v216
	v_lshlrev_b32_e32 v56, 16, v217
	v_and_b32_e32 v57, 0xffff0000, v217

; DEVI float lo2f(unsigned u) { return __uint_as_float(u << 16); }
; DEVI float hi2f(unsigned u) { return __uint_as_float(u & 0xffff0000u); }
; DEVI void phase_resid_gemm(const Params& p, const bfu* A, int lda, int nkt, const bfu* wT, int ldb, const float* resid32,
;                            float* ssq_out, float* out32, char* lds) {
;     ...
;       for (int ni = 0; ni < 4; ++ni) {
;         const int n = n0 + wn * 64 + ni * 16 + fq * 4;
;         float4 r;
;         if (resid32) r = *(const float4*)(resid32 + (long)m * 1024 + n);
;         else { const uint2 u = *(const uint2*)(xs + (long)m * LDX + n); r = make_float4(lo2f(u.x), hi2f(u.x), lo2f(u.y), hi2f(u.y)); }
;         float4 o;
;         o.x = r.x + acc[ni][mi][0]; o.y = r.y + acc[ni][mi][1]; o.z = r.z + acc[ni][mi][2]; o.w = r.w + acc[ni][mi][3];
.LBB0_343:
	v_mov_b64_e32 v[58:59], s[2:3]
	v_mad_i64_i32 v[54:55], s[28:29], v54, s95, v[58:59]
	s_andn2_b64 vcc, exec, s[36:37]
	v_lshl_add_u64 v[54:55], v[130:131], 1, v[54:55]
	s_cbranch_vccnz .LBB0_345
	v_lshl_add_u64 v[218:219], v[54:55], 0, v[254:255]
	global_load_dwordx4 v[214:217], v[218:219], off
	s_waitcnt vmcnt(0)
	v_permlane16_swap_b32_e32 v214, v216
	v_permlane16_swap_b32_e32 v215, v217
	s_nop 1
	v_lshlrev_b32_e32 v46, 16, v214
	v_and_b32_e32 v47, 0xffff0000, v214
	v_lshlrev_b32_e32 v48, 16, v215
	v_and_b32_e32 v49, 0xffff0000, v215

; DEVI float lo2f(unsigned u) { return __uint_as_float(u << 16); }
; DEVI float hi2f(unsigned u) { return __uint_as_float(u & 0xffff0000u); }
; DEVI void phase_resid_gemm(const Params& p, const bfu* A, int lda, int nkt, const bfu* wT, int ldb, const float* resid32,
;                            float* ssq_out, float* out32, char* lds) {
;     ...
;       for (int ni = 0; ni < 4; ++ni) {
;         const int n = n0 + wn * 64 + ni * 16 + fq * 4;
;         float4 r;
;         if (resid32) r = *(const float4*)(resid32 + (long)m * 1024 + n);
;         else { const uint2 u = *(const uint2*)(xs + (long)m * LDX + n); r = make_float4(lo2f(u.x), hi2f(u.x), lo2f(u.y), hi2f(u.y)); }
;         float4 o;
;         o.x = r.x + acc[ni][mi][0]; o.y = r.y + acc[ni][mi][1]; o.z = r.z + acc[ni][mi][2]; o.w = r.w + acc[ni][mi][3];
.LBB0_347:
	s_waitcnt vmcnt(0)
	v_lshlrev_b32_e32 v46, 16, v216
	v_and_b32_e32 v47, 0xffff0000, v216
	v_lshlrev_b32_e32 v48, 16, v217
	v_and_b32_e32 v49, 0xffff0000, v217

; DEVI float lo2f(unsigned u) { return __uint_as_float(u << 16); }
; DEVI float hi2f(unsigned u) { return __uint_as_float(u & 0xffff0000u); }
; DEVI void phase_resid_gemm(const Params& p, const bfu* A, int lda, int nkt, const bfu* wT, int ldb, const float* resid32,
;                            float* ssq_out, float* out32, char* lds) {
;     ...
;       for (int ni = 0; ni < 4; ++ni) {
;         const int n = n0 + wn * 64 + ni * 16 + fq * 4;
;         float4 r;
;         if (resid32) r = *(const float4*)(resid32 + (long)m * 1024 + n);
;         else { const uint2 u = *(const uint2*)(xs + (long)m * LDX + n); r = make_float4(lo2f(u.x), hi2f(u.x), lo2f(u.y), hi2f(u.y)); }
;         float4 o;
;         o.x = r.x + acc[ni][mi][0]; o.y = r.y + acc[ni][mi][1]; o.z = r.z + acc[ni][mi][2]; o.w = r.w + acc[ni][mi][3];
.LBB0_350:
	v_lshl_add_u64 v[218:219], v[54:55], 0, v[254:255]
	global_load_dwordx4 v[214:217], v[218:219], off offset:64
	s_waitcnt vmcnt(0)
	v_permlane16_swap_b32_e32 v214, v216
	v_permlane16_swap_b32_e32 v215, v217
	s_nop 1
	v_lshlrev_b32_e32 v42, 16, v214
	v_and_b32_e32 v43, 0xffff0000, v214
	v_lshlrev_b32_e32 v44, 16, v215
	v_and_b32_e32 v45, 0xffff0000, v215

; DEVI float lo2f(unsigned u) { return __uint_as_float(u << 16); }
; DEVI float hi2f(unsigned u) { return __uint_as_float(u & 0xffff0000u); }
; DEVI void phase_resid_gemm(const Params& p, const bfu* A, int lda, int nkt, const bfu* wT, int ldb, const float* resid32,
;                            float* ssq_out, float* out32, char* lds) {
;     ...
;       for (int ni = 0; ni < 4; ++ni) {
;         const int n = n0 + wn * 64 + ni * 16 + fq * 4;
;         float4 r;
;         if (resid32) r = *(const float4*)(resid32 + (long)m * 1024 + n);
;         else { const uint2 u = *(const uint2*)(xs + (long)m * LDX + n); r = make_float4(lo2f(u.x), hi2f(u.x), lo2f(u.y), hi2f(u.y)); }
;         float4 o;
;         o.x = r.x + acc[ni][mi][0]; o.y = r.y + acc[ni][mi][1]; o.z = r.z + acc[ni][mi][2]; o.w = r.w + acc[ni][mi][3];
.LBB0_353:
	s_waitcnt vmcnt(0)
	v_lshlrev_b32_e32 v38, 16, v216
	v_and_b32_e32 v39, 0xffff0000, v216
	v_lshlrev_b32_e32 v40, 16, v217
	v_and_b32_e32 v41, 0xffff0000, v217

; DEVI float lo2f(unsigned u) { return __uint_as_float(u << 16); }
; DEVI float hi2f(unsigned u) { return __uint_as_float(u & 0xffff0000u); }
; DEVI void phase_resid_gemm(const Params& p, const bfu* A, int lda, int nkt, const bfu* wT, int ldb, const float* resid32,
;                            float* ssq_out, float* out32, char* lds) {
;     ...
;       for (int ni = 0; ni < 4; ++ni) {
;         const int n = n0 + wn * 64 + ni * 16 + fq * 4;
;         float4 r;
;         if (resid32) r = *(const float4*)(resid32 + (long)m * 1024 + n);
;         else { const uint2 u = *(const uint2*)(xs + (long)m * LDX + n); r = make_float4(lo2f(u.x), hi2f(u.x), lo2f(u.y), hi2f(u.y)); }
;         float4 o;
;         o.x = r.x + acc[ni][mi][0]; o.y = r.y + acc[ni][mi][1]; o.z = r.z + acc[ni][mi][2]; o.w = r.w + acc[ni][mi][3];
.LBB0_362:
	v_mov_b64_e32 v[42:43], s[2:3]
	v_mad_i64_i32 v[38:39], s[28:29], v38, s95, v[42:43]
	s_andn2_b64 vcc, exec, s[36:37]
	v_lshl_add_u64 v[38:39], v[130:131], 1, v[38:39]
	s_cbranch_vccnz .LBB0_364
	v_lshl_add_u64 v[218:219], v[38:39], 0, v[254:255]
	global_load_dwordx4 v[214:217], v[218:219], off
	s_waitcnt vmcnt(0)
	v_permlane16_swap_b32_e32 v214, v216
	v_permlane16_swap_b32_e32 v215, v217
	s_nop 1
	v_lshlrev_b32_e32 v30, 16, v214
	v_and_b32_e32 v31, 0xffff0000, v214
	v_lshlrev_b32_e32 v32, 16, v215
	v_and_b32_e32 v33, 0xffff0000, v215

; DEVI float lo2f(unsigned u) { return __uint_as_float(u << 16); }
; DEVI float hi2f(unsigned u) { return __uint_as_float(u & 0xffff0000u); }
; DEVI void phase_resid_gemm(const Params& p, const bfu* A, int lda, int nkt, const bfu* wT, int ldb, const float* resid32,
;                            float* ssq_out, float* out32, char* lds) {
;     ...
;         const int n = n0 + wn * 64 + ni * 16 + fq * 4;
;         float4 r;
;         if (resid32) r = *(const float4*)(resid32 + (long)m * 1024 + n);
;         else { const uint2 u = *(const uint2*)(xs + (long)m * LDX + n); r = make_float4(lo2f(u.x), hi2f(u.x), lo2f(u.y), hi2f(u.y)); }
;         float4 o;
;         o.x = r.x + acc[ni][mi][0]; o.y = r.y + acc[ni][mi][1]; o.z = r.z + acc[ni][mi][2]; o.w = r.w + acc[ni][mi][3];
.LBB0_366:
	s_waitcnt vmcnt(0)
	v_lshlrev_b32_e32 v30, 16, v216
	v_and_b32_e32 v31, 0xffff0000, v216
	v_lshlrev_b32_e32 v32, 16, v217
	v_and_b32_e32 v33, 0xffff0000, v217

; DEVI float lo2f(unsigned u) { return __uint_as_float(u << 16); }
; DEVI float hi2f(unsigned u) { return __uint_as_float(u & 0xffff0000u); }
; DEVI void phase_resid_gemm(const Params& p, const bfu* A, int lda, int nkt, const bfu* wT, int ldb, const float* resid32,
;                            float* ssq_out, float* out32, char* lds) {
;     ...
;         const int n = n0 + wn * 64 + ni * 16 + fq * 4;
;         float4 r;
;         if (resid32) r = *(const float4*)(resid32 + (long)m * 1024 + n);
;         else { const uint2 u = *(const uint2*)(xs + (long)m * LDX + n); r = make_float4(lo2f(u.x), hi2f(u.x), lo2f(u.y), hi2f(u.y)); }
;         float4 o;
;         o.x = r.x + acc[ni][mi][0]; o.y = r.y + acc[ni][mi][1]; o.z = r.z + acc[ni][mi][2]; o.w = r.w + acc[ni][mi][3];
.LBB0_369:
	v_lshl_add_u64 v[218:219], v[38:39], 0, v[254:255]
	global_load_dwordx4 v[214:217], v[218:219], off offset:64
	s_waitcnt vmcnt(0)
	v_permlane16_swap_b32_e32 v214, v216
	v_permlane16_swap_b32_e32 v215, v217
	s_nop 1
	v_lshlrev_b32_e32 v26, 16, v214
	v_and_b32_e32 v27, 0xffff0000, v214
	v_lshlrev_b32_e32 v28, 16, v215
	v_and_b32_e32 v29, 0xffff0000, v215

; DEVI float lo2f(unsigned u) { return __uint_as_float(u << 16); }
; DEVI float hi2f(unsigned u) { return __uint_as_float(u & 0xffff0000u); }
; DEVI void phase_resid_gemm(const Params& p, const bfu* A, int lda, int nkt, const bfu* wT, int ldb, const float* resid32,
;                            float* ssq_out, float* out32, char* lds) {
;     ...
;         const int n = n0 + wn * 64 + ni * 16 + fq * 4;
;         float4 r;
;         if (resid32) r = *(const float4*)(resid32 + (long)m * 1024 + n);
;         else { const uint2 u = *(const uint2*)(xs + (long)m * LDX + n); r = make_float4(lo2f(u.x), hi2f(u.x), lo2f(u.y), hi2f(u.y)); }
;         float4 o;
;         o.x = r.x + acc[ni][mi][0]; o.y = r.y + acc[ni][mi][1]; o.z = r.z + acc[ni][mi][2]; o.w = r.w + acc[ni][mi][3];
.LBB0_372:
	s_waitcnt vmcnt(0)
	v_lshlrev_b32_e32 v22, 16, v216
	v_and_b32_e32 v23, 0xffff0000, v216
	v_lshlrev_b32_e32 v24, 16, v217
	v_and_b32_e32 v25, 0xffff0000, v217

; DEVI float lo2f(unsigned u) { return __uint_as_float(u << 16); }
; DEVI float hi2f(unsigned u) { return __uint_as_float(u & 0xffff0000u); }
; DEVI void phase_resid_gemm(const Params& p, const bfu* A, int lda, int nkt, const bfu* wT, int ldb, const float* resid32,
;                            float* ssq_out, float* out32, char* lds) {
;     ...
;         const int n = n0 + wn * 64 + ni * 16 + fq * 4;
;         float4 r;
;         if (resid32) r = *(const float4*)(resid32 + (long)m * 1024 + n);
;         else { const uint2 u = *(const uint2*)(xs + (long)m * LDX + n); r = make_float4(lo2f(u.x), hi2f(u.x), lo2f(u.y), hi2f(u.y)); }
;         float4 o;
;         o.x = r.x + acc[ni][mi][0]; o.y = r.y + acc[ni][mi][1]; o.z = r.z + acc[ni][mi][2]; o.w = r.w + acc[ni][mi][3];
.LBB0_381:
	v_mov_b64_e32 v[26:27], s[2:3]
	v_mad_i64_i32 v[22:23], s[28:29], v22, s95, v[26:27]
	s_andn2_b64 vcc, exec, s[36:37]
	v_lshl_add_u64 v[22:23], v[130:131], 1, v[22:23]
	s_cbranch_vccnz .LBB0_383
	v_lshl_add_u64 v[218:219], v[22:23], 0, v[254:255]
	global_load_dwordx4 v[214:217], v[218:219], off
	s_waitcnt vmcnt(0)
	v_permlane16_swap_b32_e32 v214, v216
	v_permlane16_swap_b32_e32 v215, v217
	s_nop 1
	v_lshlrev_b32_e32 v14, 16, v214
	v_and_b32_e32 v15, 0xffff0000, v214
	v_lshlrev_b32_e32 v16, 16, v215
	v_and_b32_e32 v17, 0xffff0000, v215

; DEVI float lo2f(unsigned u) { return __uint_as_float(u << 16); }
; DEVI float hi2f(unsigned u) { return __uint_as_float(u & 0xffff0000u); }
; DEVI void phase_resid_gemm(const Params& p, const bfu* A, int lda, int nkt, const bfu* wT, int ldb, const float* resid32,
;                            float* ssq_out, float* out32, char* lds) {
;     ...
;         const int n = n0 + wn * 64 + ni * 16 + fq * 4;
;         float4 r;
;         if (resid32) r = *(const float4*)(resid32 + (long)m * 1024 + n);
;         else { const uint2 u = *(const uint2*)(xs + (long)m * LDX + n); r = make_float4(lo2f(u.x), hi2f(u.x), lo2f(u.y), hi2f(u.y)); }
;         float4 o;
;         o.x = r.x + acc[ni][mi][0]; o.y = r.y + acc[ni][mi][1]; o.z = r.z + acc[ni][mi][2]; o.w = r.w + acc[ni][mi][3];
.LBB0_385:
	s_waitcnt vmcnt(0)
	v_lshlrev_b32_e32 v14, 16, v216
	v_and_b32_e32 v15, 0xffff0000, v216
	v_lshlrev_b32_e32 v16, 16, v217
	v_and_b32_e32 v17, 0xffff0000, v217

; DEVI float lo2f(unsigned u) { return __uint_as_float(u << 16); }
; DEVI float hi2f(unsigned u) { return __uint_as_float(u & 0xffff0000u); }
; DEVI void phase_resid_gemm(const Params& p, const bfu* A, int lda, int nkt, const bfu* wT, int ldb, const float* resid32,
;                            float* ssq_out, float* out32, char* lds) {
;     ...
;         const int n = n0 + wn * 64 + ni * 16 + fq * 4;
;         float4 r;
;         if (resid32) r = *(const float4*)(resid32 + (long)m * 1024 + n);
;         else { const uint2 u = *(const uint2*)(xs + (long)m * LDX + n); r = make_float4(lo2f(u.x), hi2f(u.x), lo2f(u.y), hi2f(u.y)); }
;         float4 o;
;         o.x = r.x + acc[ni][mi][0]; o.y = r.y + acc[ni][mi][1]; o.z = r.z + acc[ni][mi][2]; o.w = r.w + acc[ni][mi][3];
.LBB0_388:
	v_lshl_add_u64 v[218:219], v[22:23], 0, v[254:255]
	global_load_dwordx4 v[214:217], v[218:219], off offset:64
	s_waitcnt vmcnt(0)
	v_permlane16_swap_b32_e32 v214, v216
	v_permlane16_swap_b32_e32 v215, v217
	s_nop 1
	v_lshlrev_b32_e32 v10, 16, v214
	v_and_b32_e32 v11, 0xffff0000, v214
	v_lshlrev_b32_e32 v12, 16, v215
	v_and_b32_e32 v13, 0xffff0000, v215

; DEVI float lo2f(unsigned u) { return __uint_as_float(u << 16); }
; DEVI float hi2f(unsigned u) { return __uint_as_float(u & 0xffff0000u); }
; DEVI void phase_resid_gemm(const Params& p, const bfu* A, int lda, int nkt, const bfu* wT, int ldb, const float* resid32,
;                            float* ssq_out, float* out32, char* lds) {
;     ...
;         const int n = n0 + wn * 64 + ni * 16 + fq * 4;
;         float4 r;
;         if (resid32) r = *(const float4*)(resid32 + (long)m * 1024 + n);
;         else { const uint2 u = *(const uint2*)(xs + (long)m * LDX + n); r = make_float4(lo2f(u.x), hi2f(u.x), lo2f(u.y), hi2f(u.y)); }
;         float4 o;
;         o.x = r.x + acc[ni][mi][0]; o.y = r.y + acc[ni][mi][1]; o.z = r.z + acc[ni][mi][2]; o.w = r.w + acc[ni][mi][3];
.LBB0_391:
	s_waitcnt vmcnt(0)
	v_lshlrev_b32_e32 v6, 16, v216
	v_and_b32_e32 v7, 0xffff0000, v216
	v_lshlrev_b32_e32 v8, 16, v217
	v_and_b32_e32 v9, 0xffff0000, v217

; DEVI float bf2f(bfu h) { return __uint_as_float(((unsigned)h) << 16); }
; DEVI float sigmoidf_(float x) { return __builtin_amdgcn_rcpf(1.f + __expf(-x)); }
; DEVI void nsa_item(const Params& p, int l, int item, char* lds_raw, volatile int* nsa_cnt) {
;     ...
;   float gate[2][3];
; #pragma unroll
;   for (int g = 0; g < 2; ++g)
; #pragma unroll
;     for (int br = 0; br < 3; ++br) gate[g][br] = sigmoidf_(bf2f(myrow[C_NG + (h * 2 + g) * 3 + br]));
;     ...
; #pragma unroll
;     for (int g = 0; g < 2; ++g) {
;       const float lsum = attn_rowsum(st, g);
;       float sc = (lsum > 0.f ? 1.f / lsum : 0.f) * gate[g][1];
; #pragma unroll
;       for (int d = 0; d < 4; ++d) fin[g][d] += st.o[g][d] * sc;
;     }
;   }
;   {
;     AttnState st;
;     attn_init(st);
;     const bfu* kbase = proj + tokbase * LDP + C_KW + h * 64;
;     const bfu* vbase = (const bfu*)(p.ws + OFF_VWT) + ((long)b * 128 + h * 64) * SEQ;
;     int j = qt - 8 < 0 ? 0 : qt - 8;
;     KV_LOAD(kbase, vbase, j);
;     for (; j <= qt; ++j) {
;       KV_STORE(kvo);
;       __syncthreads();
;       if (j < qt) {
;         int jn = j + 1;
;         KV_LOAD(kbase, vbase, jn);
;       }
;       attn_step(st, qf, Kb + kvo, Vb + kvo, (j == qt) ? tokl : 63, (j == qt - 8) ? tokl : -1, fr, fq);
;       kvo ^= 64 * LS;
;     }
; #pragma unroll
;     for (int g = 0; g < 2; ++g) {
;       const float lsum = attn_rowsum(st, g);
;       float sc = (lsum > 0.f ? 1.f / lsum : 0.f) * gate[g][2];
; #pragma unroll
;       for (int d = 0; d < 4; ++d) fin[g][d] += st.o[g][d] * sc;
;     }
;   }
.LBB0_480:
	v_and_b32_e32 v0, 0xffff0000, v175
	v_mul_f32_e32 v0, 0xbfb8aa3b, v0
	v_lshlrev_b32_e32 v2, 16, v176
	v_lshlrev_b32_e32 v6, 16, v174
	v_exp_f32_e32 v0, v0
	v_mul_f32_e32 v2, 0xbfb8aa3b, v2
	v_mul_f32_e32 v6, 0xbfb8aa3b, v6
	v_exp_f32_e32 v2, v2
	v_exp_f32_e32 v12, v6
	v_add_f32_e32 v0, 1.0, v0
	v_rcp_f32_e32 v0, v0
	v_add_f32_e32 v2, 1.0, v2
	v_add_f32_e32 v12, 1.0, v12
	v_rcp_f32_e32 v13, v2
	v_rcp_f32_e32 v12, v12
	v_pk_fma_f32 v[2:3], v[0:1], v[48:49], 0 op_sel_hi:[0,1,0]
	v_pk_fma_f32 v[4:5], v[0:1], v[46:47], 0 op_sel_hi:[0,1,0]
	v_pk_fma_f32 v[6:7], v[0:1], v[44:45], 0 op_sel_hi:[0,1,0]
	v_pk_fma_f32 v[8:9], v[0:1], v[42:43], 0 op_sel_hi:[0,1,0]
	v_pk_fma_f32 v[10:11], v[0:1], v[40:41], 0 op_sel_hi:[0,1,0]
	v_pk_fma_f32 v[14:15], v[0:1], v[38:39], 0 op_sel_hi:[0,1,0]
	v_pk_fma_f32 v[16:17], v[0:1], v[32:33], 0 op_sel_hi:[0,1,0]
	v_pk_fma_f32 v[30:31], v[0:1], v[30:31], 0 op_sel_hi:[0,1,0]
	v_and_b32_e32 v0, 0xffff0000, v174
	v_pk_fma_f32 v[32:33], v[12:13], v[36:37], 0 op_sel_hi:[0,1,0]
	v_mul_f32_e32 v0, 0xbfb8aa3b, v0
	s_waitcnt lgkmcnt(0)
	v_pk_add_f32 v[36:37], v[190:191], v[192:193]
	v_exp_f32_e32 v0, v0
	v_div_scale_f32 v38, s[0:1], v37, v37, 1.0
	v_rcp_f32_e32 v39, v38
	v_add_f32_e32 v0, 1.0, v0
	v_rcp_f32_e32 v40, v0
	v_pk_fma_f32 v[34:35], v[12:13], v[34:35], 0 op_sel_hi:[0,1,0]
	v_fma_f32 v0, -v38, v39, 1.0
	v_fmac_f32_e32 v39, v0, v39
	v_div_scale_f32 v0, vcc, 1.0, v37, 1.0
	v_mul_f32_e32 v41, v0, v39
	v_fma_f32 v42, -v38, v41, v0
	v_fmac_f32_e32 v41, v42, v39
	v_fma_f32 v0, -v38, v41, v0
	v_div_fmas_f32 v0, v0, v39, v41
	v_div_fixup_f32 v0, v0, v37, 1.0
	v_cmp_lt_f32_e32 vcc, 0, v37
	s_lshl_b32 s30, s11, 1
	s_nop 0
	v_cndmask_b32_e32 v0, 0, v0, vcc
	v_mul_f32_e32 v0, v13, v0
	v_div_scale_f32 v13, s[0:1], v36, v36, 1.0
	v_rcp_f32_e32 v37, v13
	v_pk_fma_f32 v[4:5], v[54:55], v[0:1], v[4:5] op_sel_hi:[1,0,1]
	v_pk_fma_f32 v[2:3], v[56:57], v[0:1], v[2:3] op_sel_hi:[1,0,1]
	v_pk_fma_f32 v[8:9], v[70:71], v[0:1], v[8:9] op_sel_hi:[1,0,1]
	v_pk_fma_f32 v[6:7], v[72:73], v[0:1], v[6:7] op_sel_hi:[1,0,1]
	v_pk_fma_f32 v[14:15], v[74:75], v[0:1], v[14:15] op_sel_hi:[1,0,1]
	v_pk_fma_f32 v[10:11], v[76:77], v[0:1], v[10:11] op_sel_hi:[1,0,1]
	v_pk_fma_f32 v[30:31], v[78:79], v[0:1], v[30:31] op_sel_hi:[1,0,1]
	v_pk_fma_f32 v[16:17], v[80:81], v[0:1], v[16:17] op_sel_hi:[1,0,1]
	v_fma_f32 v0, -v13, v37, 1.0
	v_fmac_f32_e32 v37, v0, v37
	v_div_scale_f32 v0, vcc, 1.0, v36, 1.0
	v_mul_f32_e32 v38, v0, v37
	v_fma_f32 v39, -v13, v38, v0
	v_fmac_f32_e32 v38, v39, v37
	v_fma_f32 v0, -v13, v38, v0
	v_pk_fma_f32 v[28:29], v[12:13], v[28:29], 0 op_sel_hi:[0,1,0]
	v_pk_fma_f32 v[26:27], v[12:13], v[26:27], 0 op_sel_hi:[0,1,0]
	v_pk_fma_f32 v[24:25], v[12:13], v[24:25], 0 op_sel_hi:[0,1,0]
	v_pk_fma_f32 v[22:23], v[12:13], v[22:23], 0 op_sel_hi:[0,1,0]
	v_pk_fma_f32 v[20:21], v[12:13], v[20:21], 0 op_sel_hi:[0,1,0]
	v_pk_fma_f32 v[12:13], v[12:13], v[18:19], 0 op_sel_hi:[0,1,0]
	ds_bpermute_b32 v19, v201, v135
	ds_bpermute_b32 v18, v201, v134
	v_div_fmas_f32 v0, v0, v37, v38
	v_div_fixup_f32 v0, v0, v36, 1.0
	v_cmp_lt_f32_e32 vcc, 0, v36
	v_lshlrev_b32_e32 v38, 16, v175
	s_waitcnt lgkmcnt(0)
	v_pk_add_f32 v[18:19], v[134:135], v[18:19]
	ds_bpermute_b32 v37, v202, v19
	ds_bpermute_b32 v36, v202, v18
	v_cndmask_b32_e32 v0, 0, v0, vcc
	v_mul_f32_e32 v0, v40, v0
	v_pk_fma_f32 v[34:35], v[50:51], v[0:1], v[34:35] op_sel_hi:[1,0,1]
	v_pk_fma_f32 v[32:33], v[52:53], v[0:1], v[32:33] op_sel_hi:[1,0,1]
	v_pk_fma_f32 v[26:27], v[58:59], v[0:1], v[26:27] op_sel_hi:[1,0,1]
	v_pk_fma_f32 v[28:29], v[60:61], v[0:1], v[28:29] op_sel_hi:[1,0,1]
	v_pk_fma_f32 v[22:23], v[62:63], v[0:1], v[22:23] op_sel_hi:[1,0,1]
	v_pk_fma_f32 v[24:25], v[64:65], v[0:1], v[24:25] op_sel_hi:[1,0,1]
	v_pk_fma_f32 v[12:13], v[66:67], v[0:1], v[12:13] op_sel_hi:[1,0,1]
	v_pk_fma_f32 v[20:21], v[68:69], v[0:1], v[20:21] op_sel_hi:[1,0,1]
	v_and_b32_e32 v0, 0xffff0000, v176
	v_mul_f32_e32 v0, 0xbfb8aa3b, v0
	s_waitcnt lgkmcnt(0)
	v_pk_add_f32 v[18:19], v[18:19], v[36:37]
	v_exp_f32_e32 v0, v0
	v_mul_f32_e32 v38, 0xbfb8aa3b, v38
	v_div_scale_f32 v36, s[0:1], v19, v19, 1.0
	v_exp_f32_e32 v38, v38
	v_rcp_f32_e32 v37, v36
	v_add_f32_e32 v0, 1.0, v0
	v_rcp_f32_e32 v39, v0
	v_add_f32_e32 v0, 1.0, v38
	v_fma_f32 v38, -v36, v37, 1.0
	v_fmac_f32_e32 v37, v38, v37
	v_div_scale_f32 v38, vcc, 1.0, v19, 1.0
	v_mul_f32_e32 v40, v38, v37
	v_fma_f32 v41, -v36, v40, v38
	v_fmac_f32_e32 v40, v41, v37
	v_rcp_f32_e32 v0, v0
	v_fma_f32 v36, -v36, v40, v38
	v_div_fmas_f32 v36, v36, v37, v40
	v_div_fixup_f32 v36, v36, v19, 1.0
	v_cmp_lt_f32_e32 vcc, 0, v19
	s_nop 1
	v_cndmask_b32_e32 v19, 0, v36, vcc
	v_mul_f32_e32 v0, v0, v19
	v_div_scale_f32 v19, s[0:1], v18, v18, 1.0
	v_rcp_f32_e32 v36, v19
	v_pk_fma_f32 v[20:21], v[112:113], v[0:1], v[20:21] op_sel_hi:[1,0,1]
	v_pk_fma_f32 v[12:13], v[110:111], v[0:1], v[12:13] op_sel_hi:[1,0,1]
	v_pk_fma_f32 v[24:25], v[104:105], v[0:1], v[24:25] op_sel_hi:[1,0,1]
	v_pk_fma_f32 v[22:23], v[102:103], v[0:1], v[22:23] op_sel_hi:[1,0,1]
	v_pk_fma_f32 v[28:29], v[96:97], v[0:1], v[28:29] op_sel_hi:[1,0,1]
	v_pk_fma_f32 v[26:27], v[94:95], v[0:1], v[26:27] op_sel_hi:[1,0,1]
	v_pk_fma_f32 v[32:33], v[88:89], v[0:1], v[32:33] op_sel_hi:[1,0,1]
	v_pk_fma_f32 v[34:35], v[86:87], v[0:1], v[34:35] op_sel_hi:[1,0,1]
	v_fma_f32 v0, -v19, v36, 1.0
	v_fmac_f32_e32 v36, v0, v36
	v_div_scale_f32 v0, vcc, 1.0, v18, 1.0
	v_mul_f32_e32 v37, v0, v36
	v_fma_f32 v38, -v19, v37, v0
	v_fmac_f32_e32 v37, v38, v36
	v_fma_f32 v0, -v19, v37, v0
	v_div_fmas_f32 v0, v0, v36, v37
	v_div_fixup_f32 v0, v0, v18, 1.0
	v_cmp_lt_f32_e32 vcc, 0, v18
	v_cvt_pk_bf16_f32 v12, v12, v13
; DEVI int get_tid() { int t = threadIdx.x & 255; asm volatile("" : "+v"(t)); return t; }
; DEVI float bf2f(bfu h) { return __uint_as_float(((unsigned)h) << 16); }
; DEVI float sigmoidf_(float x) { return __builtin_amdgcn_rcpf(1.f + __expf(-x)); }
; DEVI void nsa_item(const Params& p, int l, int item, char* lds_raw, volatile int* nsa_cnt) {
;     ...
;   const int qt = 31 - (item >> 4), bh = item & 15, b = bh >> 1, h = bh & 1;
;   const int tid = get_tid(), lane = tid & 63, wid = tid >> 6, fr = lane & 15, fq = lane >> 4;
;   const bfu* proj = (const bfu*)(p.ws + OFF_PROJ);
;   const long tokbase = (long)b * SEQ;
;   const int t0 = qt * 64;
;   const int tokl = wid * 16 + fr;
;   const int mytok = t0 + tokl;
;   const bfu* myrow = proj + (tokbase + mytok) * LDP;
;   bf16x8 qf[2][2];
; #pragma unroll
;   for (int g = 0; g < 2; ++g)
; #pragma unroll
;     for (int ks = 0; ks < 2; ++ks) qf[g][ks] = *(const bf16x8*)(myrow + C_Q + (h * 2 + g) * 64 + ks * 32 + fq * 8);
;   float gate[2][3];
; #pragma unroll
;   for (int g = 0; g < 2; ++g)
; #pragma unroll
;     for (int br = 0; br < 3; ++br) gate[g][br] = sigmoidf_(bf2f(myrow[C_NG + (h * 2 + g) * 3 + br]));
;   f32x4 fin[2][4];
; #pragma unroll
;   for (int g = 0; g < 2; ++g)
; #pragma unroll
;     for (int d = 0; d < 4; ++d) fin[g][d] = f32x4{0.f, 0.f, 0.f, 0.f};
;   const int ntile = (t0 + 32 >= 1024) ? 2 : 1;
;   __syncthreads();
;   {
;     const bfu* kc = (const bfu*)(p.ws + OFF_KCMP) + (long)(b * 2 + h) * 128 * 64;
;     const bfu* vc = (const bfu*)(p.ws + OFF_VCT) + (long)(b * 2 + h) * 64 * 128;
;     for (int i = 0; i < 2 * ntile; ++i) {
;       int id = tid + 256 * i;
;       int row = id >> 3, ch = id & 7;
;       *(uint4*)(Kb + row * LS + ch * 8) = *(const uint4*)(kc + row * 64 + ch * 8);
;     ...
;   bfu* y = (bfu*)(p.ws + OFF_Y) + (tokbase + mytok) * LDX + 256 + h * 128;
; #pragma unroll
;   for (int g = 0; g < 2; ++g)
; #pragma unroll
;     for (int d = 0; d < 4; ++d) store_bf4(y + g * 64 + d * 16 + fq * 4, fin[g][d]);
	v_cvt_pk_bf16_f32 v13, v20, v21
	v_cndmask_b32_e32 v0, 0, v0, vcc
	v_mul_f32_e32 v0, v39, v0
	v_pk_fma_f32 v[18:19], v[106:107], v[0:1], v[30:31] op_sel_hi:[1,0,1]
	v_mov_b64_e32 v[30:31], s[90:91]
	v_mad_u64_u32 v[30:31], s[0:1], v184, s95, v[30:31]
	v_mad_i32_i24 v31, v185, s95, v31
	v_pk_fma_f32 v[16:17], v[108:109], v[0:1], v[16:17] op_sel_hi:[1,0,1]
	v_pk_fma_f32 v[10:11], v[100:101], v[0:1], v[10:11] op_sel_hi:[1,0,1]
	v_pk_fma_f32 v[14:15], v[98:99], v[0:1], v[14:15] op_sel_hi:[1,0,1]
	v_pk_fma_f32 v[6:7], v[92:93], v[0:1], v[6:7] op_sel_hi:[1,0,1]
	v_pk_fma_f32 v[8:9], v[90:91], v[0:1], v[8:9] op_sel_hi:[1,0,1]
	v_pk_fma_f32 v[2:3], v[84:85], v[0:1], v[2:3] op_sel_hi:[1,0,1]
	v_pk_fma_f32 v[4:5], v[82:83], v[0:1], v[4:5] op_sel_hi:[1,0,1]
	v_lshl_add_u64 v[30:31], v[30:31], 0, s[30:31]
	v_lshlrev_b32_e32 v0, 1, v203
	v_lshl_add_u64 v[30:31], v[30:31], 0, v[0:1]
	v_add_co_u32_e32 v20, vcc, s17, v30
	s_mov_b64 s[0:1], 0xa728200
	s_nop 0
	v_addc_co_u32_e32 v21, vcc, 0, v31, vcc
	v_lshl_add_u64 v[36:37], v[30:31], 0, s[0:1]
	v_lshl_add_u64 v[36:37], v[36:37], 0, v[254:255]
	v_mov_b32_e32 v246, v12
	v_mov_b32_e32 v247, v13
	v_cvt_pk_bf16_f32 v248, v22, v23
	v_cvt_pk_bf16_f32 v249, v24, v25
	v_cvt_pk_bf16_f32 v250, v26, v27
	v_cvt_pk_bf16_f32 v251, v28, v29
	v_cvt_pk_bf16_f32 v252, v34, v35
	v_cvt_pk_bf16_f32 v253, v32, v33
	s_nop 1
	v_permlane16_swap_b32_e32 v246, v248
	v_permlane16_swap_b32_e32 v247, v249
	v_permlane16_swap_b32_e32 v250, v252
	v_permlane16_swap_b32_e32 v251, v253
	s_nop 1
	global_store_dwordx4 v[36:37], v[246:249], off
	global_store_dwordx4 v[36:37], v[250:253], off offset:64
	s_nop 1
	v_cvt_pk_bf16_f32 v246, v18, v19
	v_cvt_pk_bf16_f32 v247, v16, v17
	v_cvt_pk_bf16_f32 v248, v14, v15
	v_cvt_pk_bf16_f32 v249, v10, v11
	v_cvt_pk_bf16_f32 v250, v8, v9
	v_cvt_pk_bf16_f32 v251, v6, v7
	v_cvt_pk_bf16_f32 v252, v4, v5
	v_cvt_pk_bf16_f32 v253, v2, v3
	v_readlane_b32 s0, v244, 57
	s_nop 0
	v_permlane16_swap_b32_e32 v246, v248
	v_permlane16_swap_b32_e32 v247, v249
	v_permlane16_swap_b32_e32 v250, v252
	v_permlane16_swap_b32_e32 v251, v253
	s_nop 1
	global_store_dwordx4 v[36:37], v[246:249], off offset:128
	global_store_dwordx4 v[36:37], v[250:253], off offset:192
	s_nop 1
	v_readlane_b32 s1, v244, 58
	s_load_dword s0, s[0:1], 0x0
	s_waitcnt lgkmcnt(0)
	s_lshl_b32 s0, s0, 1
	s_add_i32 s27, s0, s27
	s_cmpk_gt_i32 s27, 0x1ff
	s_cbranch_scc1 .LBB0_527
.LBB0_481:
	s_ashr_i32 s28, s27, 4
	v_mov_b32_e32 v83, v221
	s_sub_i32 s25, 31, s28
	s_lshl_b32 s4, s25, 6
	v_ashrrev_i32_e32 v0, 2, v83
	v_bfi_b32 v177, -16, v0, v83
	s_bfe_u32 s20, s27, 0x30001
	v_add_u32_e32 v84, s4, v177
	s_lshl_b32 s30, s20, 11
	v_ashrrev_i32_e32 v85, 31, v84
	v_readlane_b32 s0, v243, 0
	v_lshl_add_u64 v[184:185], s[30:31], 0, v[84:85]
	s_waitcnt lgkmcnt(0)
	v_mov_b64_e32 v[2:3], s[6:7]
	v_bfe_u32 v82, v83, 4, 2
	v_mad_u64_u32 v[18:19], s[0:1], v184, s72, v[2:3]
	s_and_b32 s23, s27, 1
	v_mad_i32_i24 v19, v185, s72, v19
	v_lshlrev_b32_e32 v0, 4, v82
	v_lshl_add_u64 v[2:3], v[18:19], 0, v[0:1]
	s_lshl_b32 s30, s23, 8
	v_lshl_add_u64 v[14:15], v[2:3], 0, s[30:31]
	s_mul_i32 s30, s23, 12
	v_lshl_add_u64 v[18:19], v[18:19], 0, s[30:31]
	s_movk_i32 s0, 0x1000
	global_load_dwordx4 v[2:5], v[14:15], off offset:1024
	global_load_dwordx4 v[6:9], v[14:15], off offset:1088
	global_load_dwordx4 v[10:13], v[14:15], off offset:1152
	s_nop 0
	global_load_dwordx4 v[14:17], v[14:15], off offset:1216
	v_add_co_u32_e32 v18, vcc, s0, v18
	s_lshl_b32 s0, s27, 14
	s_nop 0
	v_addc_co_u32_e32 v19, vcc, 0, v19, vcc
	global_load_dwordx3 v[174:176], v[18:19], off offset:1536
	s_mov_b32 s13, s22
	s_mov_b32 s22, s33
	s_mov_b32 s33, s19
	s_mov_b32 s29, s18
	s_lshl_b32 s11, s23, 7
	s_and_b32 s0, s0, 0x3c000
	v_readlane_b32 s18, v243, 14
	v_readlane_b32 s19, v243, 15
	s_add_u32 s38, s18, s0
	s_addc_u32 s39, s19, 0
	s_cmpk_gt_u32 s4, 0x3df
	s_cselect_b64 s[36:37], -1, 0
	v_lshlrev_b32_e32 v0, 3, v83
	s_and_b64 s[4:5], s[36:37], exec
	v_and_b32_e32 v18, 56, v0
	s_cselect_b32 s4, 4, 2
	v_lshlrev_b32_e32 v0, 1, v18
	v_and_b32_e32 v153, 15, v83
	v_lshlrev_b32_e32 v93, 3, v82
	v_lshl_add_u64 v[20:21], s[38:39], 0, v[0:1]
	v_add_u32_e32 v0, s26, v0
	s_mov_b32 s1, s4
	v_mov_b32_e32 v19, v83
	s_movk_i32 s5, 0x90
	s_waitcnt vmcnt(0)
	s_barrier
	v_ashrrev_i32_e32 v26, 3, v83
	v_lshlrev_b32_e32 v22, 7, v26
	v_mov_b32_e32 v23, 0
	s_mov_b64 s[38:39], 0x1000
	v_lshl_add_u64 v[22:23], v[20:21], 0, v[22:23]
	v_mad_u32_u24 v26, v26, s5, v0
	global_load_dwordx4 v[246:249], v[22:23], off
	v_lshl_add_u64 v[22:23], v[22:23], 0, s[38:39]
	global_load_dwordx4 v[250:253], v[22:23], off
	s_cmp_eq_u32 s1, 4
	s_cbranch_scc0 .Lcmpk_two
	v_lshl_add_u64 v[22:23], v[22:23], 0, s[38:39]
	global_load_dwordx4 v[234:237], v[22:23], off
	v_lshl_add_u64 v[22:23], v[22:23], 0, s[38:39]
	global_load_dwordx4 v[238:241], v[22:23], off
	s_waitcnt vmcnt(3)
	ds_write_b128 v26, v[246:249]
	s_waitcnt vmcnt(2)
	ds_write_b128 v26, v[250:253] offset:4608
	s_waitcnt vmcnt(1)
	ds_write_b128 v26, v[234:237] offset:9216
	s_waitcnt vmcnt(0)
	ds_write_b128 v26, v[238:241] offset:13824
	s_branch .Lcmpk_done
; DEVI void nsa_item(const Params& p, int l, int item, char* lds_raw, volatile int* nsa_cnt) {
;     ...
;     const bfu* kc = (const bfu*)(p.ws + OFF_KCMP) + (long)(b * 2 + h) * 128 * 64;
;     const bfu* vc = (const bfu*)(p.ws + OFF_VCT) + (long)(b * 2 + h) * 64 * 128;
;     for (int i = 0; i < 2 * ntile; ++i) {
;       int id = tid + 256 * i;
;       int row = id >> 3, ch = id & 7;
;       *(uint4*)(Kb + row * LS + ch * 8) = *(const uint4*)(kc + row * 64 + ch * 8);
;     }
;     for (int i = 0; i < 2 * ntile; ++i) {
;       int id = tid + 256 * i;
;       int tt = id >> 9, d = (id >> 3) & 63, ch = id & 7;
;       *(uint4*)(Vb + tt * 64 * LS + d * LS + ch * 8) = *(const uint4*)(vc + d * 128 + tt * 64 + ch * 8);
;     }
;   }
;   __syncthreads();
;   {
;     f32x4 s[2][2][4];
;     compute_S(s[0], qf, Kb, fr, fq);
;     if (ntile == 2) compute_S(s[1], qf, Kb + 64 * LS, fr, fq);
.Lcmpk_two:
	s_waitcnt vmcnt(1)
	ds_write_b128 v26, v[246:249]
	s_waitcnt vmcnt(0)
	ds_write_b128 v26, v[250:253] offset:4608
.Lcmpk_done:
	v_readlane_b32 s1, v243, 16
	s_add_u32 s0, s1, s0
	v_readlane_b32 s1, v243, 17
	s_mov_b64 s[18:19], s[6:7]
	s_addc_u32 s1, s1, 0
	v_ashrrev_i32_e32 v24, 3, v83
	v_lshlrev_b32_e32 v0, 1, v18
	v_lshl_add_u32 v20, v24, 8, v0
	v_mov_b32_e32 v21, 0
	s_mov_b64 s[38:39], 0x2000
	v_lshl_add_u64 v[20:21], s[0:1], 0, v[20:21]
	v_mul_u32_u24_e32 v24, 0x90, v24
	v_add3_u32 v24, v24, v0, s26
	global_load_dwordx4 v[246:249], v[20:21], off
	v_lshl_add_u64 v[22:23], v[20:21], 0, s[38:39]
	global_load_dwordx4 v[250:253], v[22:23], off
	s_cmp_eq_u32 s4, 4
	s_cbranch_scc0 .Lcmpv_two
	global_load_dwordx4 v[234:237], v[20:21], off offset:128
	global_load_dwordx4 v[238:241], v[22:23], off offset:128
	s_waitcnt vmcnt(3)
	ds_write_b128 v24, v[246:249] offset:18432
	s_waitcnt vmcnt(2)
	ds_write_b128 v24, v[250:253] offset:23040
	s_waitcnt vmcnt(1)
	ds_write_b128 v24, v[234:237] offset:27648
	s_waitcnt vmcnt(0)
	ds_write_b128 v24, v[238:241] offset:32256
	s_branch .Lcmpv_done
.Lcmpv_two:
	s_waitcnt vmcnt(1)
	ds_write_b128 v24, v[246:249] offset:18432
	s_waitcnt vmcnt(0)
	ds_write_b128 v24, v[250:253] offset:23040
.Lcmpv_done:
	s_mov_b32 s4, 0
	v_mul_u32_u24_e32 v18, 0x48, v153
	v_lshlrev_b32_e32 v183, 1, v93
	v_lshlrev_b32_e32 v199, 1, v18
	v_add3_u32 v155, s26, v183, v199
	s_waitcnt lgkmcnt(0)
	s_barrier
	ds_read_b128 v[18:21], v155
	ds_read_b128 v[54:57], v155 offset:64
	ds_read_b128 v[26:29], v155 offset:2304
	ds_read_b128 v[34:37], v155 offset:4608
	ds_read_b128 v[42:45], v155 offset:6912
	s_waitcnt lgkmcnt(4)
	v_mfma_f32_16x16x32_bf16 v[22:25], v[18:21], v[2:5], 0
	s_mov_b64 s[16:17], s[2:3]
	s_mov_b64 s[6:7], s[96:97]
	s_mov_b32 s24, s87
	s_waitcnt lgkmcnt(3)
	v_mfma_f32_16x16x32_bf16 v[50:53], v[54:57], v[6:9], v[22:25]
	s_mov_b32 s30, s86
	s_and_b64 vcc, s[36:37], exec
	v_mov_b32_e32 v78, 0
	ds_read_b128 v[22:25], v155 offset:2368
	v_mfma_f32_16x16x32_bf16 v[18:21], v[18:21], v[10:13], 0
	v_mov_b32_e32 v79, 0
	v_mov_b32_e32 v80, 0
	v_mov_b32_e32 v81, 0
	s_waitcnt lgkmcnt(3)
	v_mfma_f32_16x16x32_bf16 v[30:33], v[26:29], v[2:5], 0
	v_mov_b32_e32 v66, 0
	v_mov_b32_e32 v67, 0
	v_mov_b32_e32 v68, 0
	v_mfma_f32_16x16x32_bf16 v[26:29], v[26:29], v[10:13], 0
	v_mov_b32_e32 v69, 0
	v_mov_b32_e32 v70, 0
	v_mov_b32_e32 v71, 0
	v_mfma_f32_16x16x32_bf16 v[18:21], v[54:57], v[14:17], v[18:21]
	v_mov_b32_e32 v72, 0
	v_mov_b32_e32 v73, 0
	v_mov_b32_e32 v74, 0
	s_waitcnt lgkmcnt(0)
	v_mfma_f32_16x16x32_bf16 v[54:57], v[22:25], v[6:9], v[30:33]
	v_mov_b32_e32 v75, 0
	v_mov_b32_e32 v76, 0
	v_mov_b32_e32 v77, 0
	v_mfma_f32_16x16x32_bf16 v[22:25], v[22:25], v[14:17], v[26:29]
	ds_read_b128 v[30:33], v155 offset:6976
	s_nop 1
	ds_read_b128 v[26:29], v155 offset:4672
	v_mfma_f32_16x16x32_bf16 v[38:41], v[34:37], v[2:5], 0
	v_mfma_f32_16x16x32_bf16 v[34:37], v[34:37], v[10:13], 0
	v_mfma_f32_16x16x32_bf16 v[46:49], v[42:45], v[2:5], 0
	v_mfma_f32_16x16x32_bf16 v[42:45], v[42:45], v[10:13], 0
	s_waitcnt lgkmcnt(0)
	v_mfma_f32_16x16x32_bf16 v[58:61], v[26:29], v[6:9], v[38:41]
	v_mfma_f32_16x16x32_bf16 v[26:29], v[26:29], v[14:17], v[34:37]
	s_nop 1
	v_mov_b32_e32 v38, 0
	v_mov_b32_e32 v39, 0
	v_mov_b32_e32 v40, 0
	v_mfma_f32_16x16x32_bf16 v[62:65], v[30:33], v[6:9], v[46:49]
	v_mov_b32_e32 v41, 0
	v_mov_b32_e32 v34, 0
	v_mov_b32_e32 v35, 0
	v_mfma_f32_16x16x32_bf16 v[30:33], v[30:33], v[14:17], v[42:45]
	v_mov_b32_e32 v46, 0
	v_mov_b32_e32 v47, 0
	v_mov_b32_e32 v48, 0
	v_mov_b32_e32 v49, 0
	v_mov_b32_e32 v42, 0
	v_mov_b32_e32 v43, 0
	v_mov_b32_e32 v44, 0
	v_mov_b32_e32 v45, 0
	v_mov_b32_e32 v36, 0
	v_mov_b32_e32 v37, 0
	s_cbranch_vccz .LBB0_487
	ds_read_b128 v[66:69], v155 offset:13824
	ds_read_b128 v[34:37], v155 offset:9216
	ds_read_b128 v[42:45], v155 offset:11520
	s_waitcnt lgkmcnt(2)
	v_mfma_f32_16x16x32_bf16 v[78:81], v[66:69], v[2:5], 0
	v_mfma_f32_16x16x32_bf16 v[86:89], v[66:69], v[10:13], 0
	ds_read_b128 v[66:69], v155 offset:16128
	s_waitcnt lgkmcnt(0)
	v_mfma_f32_16x16x32_bf16 v[94:97], v[66:69], v[2:5], 0
	v_mfma_f32_16x16x32_bf16 v[98:101], v[66:69], v[10:13], 0
	ds_read_b128 v[66:69], v155 offset:9280
	v_mfma_f32_16x16x32_bf16 v[38:41], v[34:37], v[2:5], 0
	s_waitcnt lgkmcnt(0)
	v_mfma_f32_16x16x32_bf16 v[74:77], v[66:69], v[6:9], v[38:41]
	s_nop 5
	ds_read_b128 v[38:41], v155 offset:11584
	v_mfma_f32_16x16x32_bf16 v[46:49], v[42:45], v[2:5], 0
	v_mfma_f32_16x16x32_bf16 v[42:45], v[42:45], v[10:13], 0
	s_waitcnt lgkmcnt(0)
	v_mfma_f32_16x16x32_bf16 v[70:73], v[38:41], v[6:9], v[46:49]
	v_mfma_f32_16x16x32_bf16 v[38:41], v[38:41], v[14:17], v[42:45]
	s_nop 3
	ds_read_b128 v[46:49], v155 offset:16192
	ds_read_b128 v[42:45], v155 offset:13888
	v_mfma_f32_16x16x32_bf16 v[34:37], v[34:37], v[10:13], 0
	v_mfma_f32_16x16x32_bf16 v[34:37], v[66:69], v[14:17], v[34:37]
	s_waitcnt lgkmcnt(0)
	v_mfma_f32_16x16x32_bf16 v[66:69], v[42:45], v[6:9], v[78:81]
	v_mfma_f32_16x16x32_bf16 v[42:45], v[42:45], v[14:17], v[86:89]
	v_mfma_f32_16x16x32_bf16 v[78:81], v[46:49], v[6:9], v[94:97]
	v_mfma_f32_16x16x32_bf16 v[46:49], v[46:49], v[14:17], v[98:101]
